# compress GEMM operands staged through LDS with coalesced loads; DPP quad shuffles in NSA cmp2 importance sums; DPP wave sums in LayerNorm; prep_x loop unrolled x4
# speedup vs baseline: 1.0475x; 1.0103x over previous
; __device__ __forceinline__ int otid() { int t = threadIdx.x; asm volatile("" : "+v"(t)); return t; }
; __device__ __forceinline__ int obid() { int t = blockIdx.x; asm volatile("" : "+s"(t)); return t; }
; __device__ __forceinline__ unsigned cvt_pk(float lo, float hi) { f32x2_t v = {lo, hi}; bf16x2_t b = __builtin_convertvector(v, bf16x2_t); return __builtin_bit_cast(unsigned, b); }
; __device__ __forceinline__ void prep_x(const Params& P) {
;     const size_t n4 = (size_t)M * DM / 4; const f32x4* xi = (const f32x4*)P.in[0]; f32x4* xo = (f32x4*)P.out; u32x2* xn = (u32x2*)(P.ws + WS_XN);
;     for (size_t i = (size_t)obid() * NT + otid(); i < n4; i += (size_t)gridDim.x * NT) {
;         const f32x4 v = xi[i]; xo[i] = v; u32x2 w; w.x = cvt_pk(v[0], v[1]); w.y = cvt_pk(v[2], v[3]); xn[i] = w;
;     }
; }
.LBB0_5:
	s_or_b64 exec, exec, s[4:5]
	v_readlane_b32 s4, v252, 0
	s_load_dwordx16 s[36:51], s[0:1], 0x0
	s_mov_b32 s10, s4
	s_ashr_i32 s11, s10, 31
	v_mov_b32_e32 v6, v193
	s_lshl_b64 s[4:5], s[10:11], 9
	s_nop 0
	v_ashrrev_i32_e32 v7, 31, v6
	v_lshl_add_u64 v[2:3], s[4:5], 0, v[6:7]
	s_mov_b64 s[4:5], 0x800000
	v_cmp_gt_u64_e32 vcc, s[4:5], v[2:3]
	s_and_saveexec_b64 s[4:5], vcc
	s_cbranch_execz .LBB0_8
	s_mov_b32 s13, 0
	s_mov_b32 s12, s22
	s_lshl_b64 s[8:9], s[10:11], 13
	s_lshl_b64 s[6:7], s[12:13], 9
	v_lshl_add_u64 v[4:5], v[6:7], 4, s[8:9]
	s_lshl_b64 s[8:9], s[12:13], 13
	s_lshl_b64 s[10:11], s[10:11], 12
	s_add_u32 s10, s20, s10
	s_addc_u32 s11, s21, s11
	v_lshl_add_u64 v[6:7], v[6:7], 3, s[10:11]
	s_mov_b64 s[10:11], 0x3600000
	v_lshl_add_u64 v[6:7], v[6:7], 0, s[10:11]
	s_lshl_b64 s[10:11], s[12:13], 12
	s_mov_b64 s[12:13], 0
	s_mov_b64 s[14:15], 0x7fffff
	s_lshl_b64 s[100:101], s[6:7], 2
	s_sub_u32 s98, s100, s6
	s_subb_u32 s99, s101, s7
	s_waitcnt lgkmcnt(0)
.Lpx4:
	v_lshl_add_u64 v[26:27], v[2:3], 0, s[98:99]
	v_cmp_ge_u64_e32 vcc, s[14:15], v[26:27]
	s_nop 3
	s_cmp_eq_u64 vcc, exec
	s_cbranch_scc0 .Lpx_rem
	v_lshl_add_u64 v[28:29], v[4:5], 0, s[8:9]
	v_lshl_add_u64 v[30:31], v[28:29], 0, s[8:9]
	v_lshl_add_u64 v[32:33], v[30:31], 0, s[8:9]
	v_lshl_add_u64 v[8:9], s[36:37], 0, v[4:5]
	global_load_dwordx4 v[14:17], v[8:9], off
	v_lshl_add_u64 v[8:9], s[36:37], 0, v[28:29]
	global_load_dwordx4 v[18:21], v[8:9], off
	v_lshl_add_u64 v[8:9], s[36:37], 0, v[30:31]
	global_load_dwordx4 v[22:25], v[8:9], off
	v_lshl_add_u64 v[8:9], s[36:37], 0, v[32:33]
	global_load_dwordx4 v[34:37], v[8:9], off
	s_waitcnt vmcnt(3)
	v_lshl_add_u64 v[8:9], s[94:95], 0, v[4:5]
	global_store_dwordx4 v[8:9], v[14:17], off
	v_cvt_pk_bf16_f32 v10, v14, v15
	v_cvt_pk_bf16_f32 v11, v16, v17
	global_store_dwordx2 v[6:7], v[10:11], off
	v_lshl_add_u64 v[6:7], v[6:7], 0, s[10:11]
	s_waitcnt vmcnt(4)
	v_lshl_add_u64 v[8:9], s[94:95], 0, v[28:29]
	global_store_dwordx4 v[8:9], v[18:21], off
	v_cvt_pk_bf16_f32 v12, v18, v19
	v_cvt_pk_bf16_f32 v13, v20, v21
	global_store_dwordx2 v[6:7], v[12:13], off
	v_lshl_add_u64 v[6:7], v[6:7], 0, s[10:11]
	s_waitcnt vmcnt(5)
	v_lshl_add_u64 v[8:9], s[94:95], 0, v[30:31]
	global_store_dwordx4 v[8:9], v[22:25], off
	v_cvt_pk_bf16_f32 v10, v22, v23
	v_cvt_pk_bf16_f32 v11, v24, v25
	global_store_dwordx2 v[6:7], v[10:11], off
	v_lshl_add_u64 v[6:7], v[6:7], 0, s[10:11]
	s_waitcnt vmcnt(6)
	v_lshl_add_u64 v[8:9], s[94:95], 0, v[32:33]
	global_store_dwordx4 v[8:9], v[34:37], off
	v_cvt_pk_bf16_f32 v12, v34, v35
	v_cvt_pk_bf16_f32 v13, v36, v37
	global_store_dwordx2 v[6:7], v[12:13], off
	v_lshl_add_u64 v[6:7], v[6:7], 0, s[10:11]
	v_lshl_add_u64 v[4:5], v[32:33], 0, s[8:9]
	v_lshl_add_u64 v[2:3], v[2:3], 0, s[100:101]
	s_branch .Lpx4
.Lpx_rem:
	v_cmp_ge_u64_e32 vcc, s[14:15], v[2:3]
	s_nop 1
	s_and_b64 exec, exec, vcc
	s_cbranch_execz .LBB0_8

; __device__ __forceinline__ f32x16 mfma32(bf16x8 a, bf16x8 b, f32x16 c) { return __builtin_amdgcn_mfma_f32_32x32x16_bf16(a, b, c, 0, 0, 0); }
; __device__ __forceinline__ void compress_phase(lptr L, const Params& P, int l) {
;     ...
;     for (int u = blockIdx.x; u < 256; u += gridDim.x) {
;         const int src = u >> 7, bg = (u >> 3) & 15, rt = u & 7, b = bg >> 1, g = bg & 1, i0 = 32 * rt;
;         const int coff = (src ? C_VCMP : C_KCMP) + g * 64;
;         const bf16_t* Zb = Z + (size_t)b * SEQ * ZLD + coff + 8 * hl;
;         const bf16_t* B1 = (const bf16_t*)(ws + W_C1) + (size_t)src * 256 * 2048 + (size_t)(32 * wave + n) * 2048 + 8 * hl;
;         f32x16 acc = {};
;         const int tok0 = 16 * (i0 + n);
; #pragma unroll 2
;         for (int p = 0; p < 32; ++p) {
;             int tok = tok0 + p; tok = tok > SEQ - 1 ? SEQ - 1 : tok;
;             const bf16_t* ar = Zb + (size_t)tok * ZLD; const bf16_t* br = B1 + p * 64;
; #pragma unroll
;             for (int s = 0; s < 4; ++s) acc = mfma32(*(const bf16x8*)(ar + 16 * s), *(const bf16x8*)(br + 16 * s), acc);
;         }
.LBB0_203:
	v_readfirstlane_b32 s26, v62
	v_readfirstlane_b32 s27, v63
	s_and_b32 s3, s6, 7
	s_lshl_b32 s3, s3, 9
	v_lshrrev_b32_e32 v98, 6, v193
	v_readlane_b32 s30, v254, 61
	v_readlane_b32 s31, v254, 62
	v_readfirstlane_b32 s29, v98
	s_lshl_b32 s28, s0, 20
	s_add_u32 s30, s30, s28
	s_addc_u32 s31, s31, 0
	s_lshl_b32 s28, s29, 17
	s_add_u32 s30, s30, s28
	s_addc_u32 s31, s31, 0
	s_sub_u32 s30, s30, 0x80
	s_subb_u32 s31, s31, 0
	s_mul_i32 s28, s29, 4608
	s_add_u32 s28, s28, 93440
	v_lshrrev_b32_e32 v99, 3, v222
	v_and_b32_e32 v100, 7, v222
	v_lshlrev_b32_e32 v100, 4, v100
	v_lshl_add_u32 v144, v99, 12, v100
	v_add_u32_e32 v145, 0x8000, v144
	v_add_u32_e32 v146, 0x10000, v144
	v_add_u32_e32 v147, 0x18000, v144
	v_mov_b32_e32 v101, 0x90
	v_mad_u32_u24 v143, v99, v101, v100
	v_add_u32_e32 v143, s28, v143
	v_and_b32_e32 v99, 31, v222
	v_lshrrev_b32_e32 v100, 5, v222
	v_lshlrev_b32_e32 v100, 4, v100
	v_mad_u32_u24 v141, v99, v101, v100
	v_add_u32_e32 v142, s28, v141
	v_lshrrev_b32_e32 v98, 3, v193
	v_and_b32_e32 v99, 7, v193
	v_lshlrev_b32_e32 v99, 4, v99
	v_and_b32_e32 v100, 15, v98
	v_lshrrev_b32_e32 v102, 4, v98
	v_mad_u32_u24 v100, v100, 33, v102
	v_mad_u32_u24 v100, v100, v101, v99
	v_add_u32_e32 v102, s3, v98
	v_add_u32_e32 v103, 0, v102
	v_min_u32_e32 v103, 0xfff, v103
	v_mul_u32_u24_e32 v103, 0x1c40, v103
	v_add_u32_e32 v103, v103, v99
	global_load_dwordx4 v[148:151], v103, s[26:27]
	v_add_u32_e32 v103, 64, v102
	v_min_u32_e32 v103, 0xfff, v103
	v_mul_u32_u24_e32 v103, 0x1c40, v103
	v_add_u32_e32 v103, v103, v99
	global_load_dwordx4 v[152:155], v103, s[26:27]
	v_add_u32_e32 v103, 128, v102
	v_min_u32_e32 v103, 0xfff, v103
	v_mul_u32_u24_e32 v103, 0x1c40, v103
	v_add_u32_e32 v103, v103, v99
	global_load_dwordx4 v[156:159], v103, s[26:27]
	v_add_u32_e32 v103, 192, v102
	v_min_u32_e32 v103, 0xfff, v103
	v_mul_u32_u24_e32 v103, 0x1c40, v103
	v_add_u32_e32 v103, v103, v99
	global_load_dwordx4 v[226:229], v103, s[26:27]
	v_add_u32_e32 v103, 256, v102
	v_min_u32_e32 v103, 0xfff, v103
	v_mul_u32_u24_e32 v103, 0x1c40, v103
	v_add_u32_e32 v103, v103, v99
	global_load_dwordx4 v[230:233], v103, s[26:27]
	v_add_u32_e32 v103, 320, v102
	v_min_u32_e32 v103, 0xfff, v103
	v_mul_u32_u24_e32 v103, 0x1c40, v103
	v_add_u32_e32 v103, v103, v99
	global_load_dwordx4 v[234:237], v103, s[26:27]
	v_add_u32_e32 v103, 384, v102
	v_min_u32_e32 v103, 0xfff, v103
	v_mul_u32_u24_e32 v103, 0x1c40, v103
	v_add_u32_e32 v103, v103, v99
	global_load_dwordx4 v[238:241], v103, s[26:27]
	v_add_u32_e32 v103, 448, v102
	v_min_u32_e32 v103, 0xfff, v103
	v_mul_u32_u24_e32 v103, 0x1c40, v103
	v_add_u32_e32 v103, v103, v99
	global_load_dwordx4 v[242:245], v103, s[26:27]
	v_cmp_gt_u32_e32 vcc, 16, v98
	v_mov_b32_e32 v139, 0x200
	s_nop 1
	v_cndmask_b32_e32 v139, 0, v139, vcc
	v_add_u32_e32 v103, v139, v102
	v_min_u32_e32 v103, 0xfff, v103
	v_mul_u32_u24_e32 v103, 0x1c40, v103
	v_add_u32_e32 v103, v103, v99
	global_load_dwordx4 v[246:249], v103, s[26:27]
	v_mov_b32_e32 v138, 0x1200
	v_cndmask_b32_e32 v138, 0, v138, vcc
	v_add_u32_e32 v138, v138, v100
	global_load_dwordx4 v[104:107], v144, s[30:31]
	global_load_dwordx4 v[108:111], v145, s[30:31]
	global_load_dwordx4 v[112:115], v146, s[30:31]
	global_load_dwordx4 v[116:119], v147, s[30:31]
	s_add_u32 s30, s30, 0x80
	s_addc_u32 s31, s31, 0
	global_load_dwordx4 v[120:123], v144, s[30:31]
	global_load_dwordx4 v[124:127], v145, s[30:31]
	global_load_dwordx4 v[128:131], v146, s[30:31]
	global_load_dwordx4 v[132:135], v147, s[30:31]
	s_add_u32 s30, s30, 0x80
	s_addc_u32 s31, s31, 0
	global_load_dwordx4 v[170:173], v144, s[30:31]
	global_load_dwordx4 v[174:177], v145, s[30:31]
	global_load_dwordx4 v[178:181], v146, s[30:31]
	global_load_dwordx4 v[182:185], v147, s[30:31]
	s_add_u32 s30, s30, 0x80
	s_addc_u32 s31, s31, 0
	global_load_dwordx4 v[194:197], v144, s[30:31]
	global_load_dwordx4 v[198:201], v145, s[30:31]
	global_load_dwordx4 v[202:205], v146, s[30:31]
	global_load_dwordx4 v[206:209], v147, s[30:31]
	s_add_u32 s30, s30, 0x80
	s_addc_u32 s31, s31, 0
	s_waitcnt vmcnt(16)
	ds_write_b128 v100, v[148:151] offset:17408
	ds_write_b128 v100, v[152:155] offset:17984
	ds_write_b128 v100, v[156:159] offset:18560
	ds_write_b128 v100, v[226:229] offset:19136
	ds_write_b128 v100, v[230:233] offset:19712
	ds_write_b128 v100, v[234:237] offset:20288
	ds_write_b128 v100, v[238:241] offset:20864
	ds_write_b128 v100, v[242:245] offset:21440
	ds_write_b128 v138, v[246:249] offset:17408
	s_waitcnt vmcnt(12)
	ds_write_b128 v143, v[104:107] offset:0
	ds_write_b128 v143, v[108:111] offset:1152
	ds_write_b128 v143, v[112:115] offset:2304
	ds_write_b128 v143, v[116:119] offset:3456
	s_waitcnt lgkmcnt(0)
	s_barrier
	s_mov_b32 s28, 0
	s_mov_b32 s29, 0
; __device__ __forceinline__ f32x16 mfma32(bf16x8 a, bf16x8 b, f32x16 c) { return __builtin_amdgcn_mfma_f32_32x32x16_bf16(a, b, c, 0, 0, 0); }
; __device__ __forceinline__ void compress_phase(lptr L, const Params& P, int l) {
;     ...
;         for (int p = 0; p < 32; ++p) {
;             int tok = tok0 + p; tok = tok > SEQ - 1 ? SEQ - 1 : tok;
;             const bf16_t* ar = Zb + (size_t)tok * ZLD; const bf16_t* br = B1 + p * 64;
; #pragma unroll
;             for (int s = 0; s < 4; ++s) acc = mfma32(*(const bf16x8*)(ar + 16 * s), *(const bf16x8*)(br + 16 * s), acc);
;         }
.Lcl_loop:
	v_add_u32_e32 v140, s28, v141
	ds_read_b128 v[226:229], v140 offset:17408
	ds_read_b128 v[230:233], v140 offset:17440
	ds_read_b128 v[234:237], v140 offset:17472
	ds_read_b128 v[238:241], v140 offset:17504
	ds_read_b128 v[242:245], v142 offset:0
	ds_read_b128 v[246:249], v142 offset:32
	ds_read_b128 v[186:189], v142 offset:64
	ds_read_b128 v[210:213], v142 offset:96
	s_waitcnt vmcnt(8)
	ds_write_b128 v143, v[120:123] offset:0
	ds_write_b128 v143, v[124:127] offset:1152
	ds_write_b128 v143, v[128:131] offset:2304
	ds_write_b128 v143, v[132:135] offset:3456
	global_load_dwordx4 v[104:107], v144, s[30:31]
	global_load_dwordx4 v[108:111], v145, s[30:31]
	global_load_dwordx4 v[112:115], v146, s[30:31]
	global_load_dwordx4 v[116:119], v147, s[30:31]
	s_add_u32 s30, s30, 0x80
	s_addc_u32 s31, s31, 0
	s_waitcnt lgkmcnt(4)
	v_mfma_f32_32x32x16_bf16 v[2:17], v[226:229], v[242:245], v[2:17]
	v_mfma_f32_32x32x16_bf16 v[2:17], v[230:233], v[246:249], v[2:17]
	v_mfma_f32_32x32x16_bf16 v[2:17], v[234:237], v[186:189], v[2:17]
	v_mfma_f32_32x32x16_bf16 v[2:17], v[238:241], v[210:213], v[2:17]
	ds_read_b128 v[226:229], v140 offset:22160
	ds_read_b128 v[230:233], v140 offset:22192
	ds_read_b128 v[234:237], v140 offset:22224
	ds_read_b128 v[238:241], v140 offset:22256
	ds_read_b128 v[242:245], v142 offset:0
	ds_read_b128 v[246:249], v142 offset:32
	ds_read_b128 v[186:189], v142 offset:64
	ds_read_b128 v[210:213], v142 offset:96
	s_waitcnt vmcnt(8)
	ds_write_b128 v143, v[170:173] offset:0
	ds_write_b128 v143, v[174:177] offset:1152
	ds_write_b128 v143, v[178:181] offset:2304
	ds_write_b128 v143, v[182:185] offset:3456
	global_load_dwordx4 v[120:123], v144, s[30:31]
	global_load_dwordx4 v[124:127], v145, s[30:31]
	global_load_dwordx4 v[128:131], v146, s[30:31]
	global_load_dwordx4 v[132:135], v147, s[30:31]
	s_add_u32 s30, s30, 0x80
	s_addc_u32 s31, s31, 0
	s_waitcnt lgkmcnt(4)
	v_mfma_f32_32x32x16_bf16 v[2:17], v[226:229], v[242:245], v[2:17]
	v_mfma_f32_32x32x16_bf16 v[2:17], v[230:233], v[246:249], v[2:17]
	v_mfma_f32_32x32x16_bf16 v[2:17], v[234:237], v[186:189], v[2:17]
	v_mfma_f32_32x32x16_bf16 v[2:17], v[238:241], v[210:213], v[2:17]
	ds_read_b128 v[226:229], v140 offset:26912
	ds_read_b128 v[230:233], v140 offset:26944
	ds_read_b128 v[234:237], v140 offset:26976
	ds_read_b128 v[238:241], v140 offset:27008
	ds_read_b128 v[242:245], v142 offset:0
	ds_read_b128 v[246:249], v142 offset:32
	ds_read_b128 v[186:189], v142 offset:64
	ds_read_b128 v[210:213], v142 offset:96
	s_waitcnt vmcnt(8)
	ds_write_b128 v143, v[194:197] offset:0
	ds_write_b128 v143, v[198:201] offset:1152
	ds_write_b128 v143, v[202:205] offset:2304
	ds_write_b128 v143, v[206:209] offset:3456
	global_load_dwordx4 v[170:173], v144, s[30:31]
	global_load_dwordx4 v[174:177], v145, s[30:31]
	global_load_dwordx4 v[178:181], v146, s[30:31]
	global_load_dwordx4 v[182:185], v147, s[30:31]
	s_add_u32 s30, s30, 0x80
	s_addc_u32 s31, s31, 0
	s_waitcnt lgkmcnt(4)
	v_mfma_f32_32x32x16_bf16 v[2:17], v[226:229], v[242:245], v[2:17]
	v_mfma_f32_32x32x16_bf16 v[2:17], v[230:233], v[246:249], v[2:17]
	v_mfma_f32_32x32x16_bf16 v[2:17], v[234:237], v[186:189], v[2:17]
	v_mfma_f32_32x32x16_bf16 v[2:17], v[238:241], v[210:213], v[2:17]
	ds_read_b128 v[226:229], v140 offset:31664
	ds_read_b128 v[230:233], v140 offset:31696
	ds_read_b128 v[234:237], v140 offset:31728
	ds_read_b128 v[238:241], v140 offset:31760
	ds_read_b128 v[242:245], v142 offset:0
	ds_read_b128 v[246:249], v142 offset:32
	ds_read_b128 v[186:189], v142 offset:64
	ds_read_b128 v[210:213], v142 offset:96
	s_waitcnt vmcnt(8)
	ds_write_b128 v143, v[104:107] offset:0
	ds_write_b128 v143, v[108:111] offset:1152
	ds_write_b128 v143, v[112:115] offset:2304
	ds_write_b128 v143, v[116:119] offset:3456
	global_load_dwordx4 v[194:197], v144, s[30:31]
	global_load_dwordx4 v[198:201], v145, s[30:31]
	global_load_dwordx4 v[202:205], v146, s[30:31]
	global_load_dwordx4 v[206:209], v147, s[30:31]
	s_add_u32 s30, s30, 0x80
	s_addc_u32 s31, s31, 0
	s_waitcnt lgkmcnt(4)
	v_mfma_f32_32x32x16_bf16 v[2:17], v[226:229], v[242:245], v[2:17]
	v_mfma_f32_32x32x16_bf16 v[2:17], v[230:233], v[246:249], v[2:17]
	v_mfma_f32_32x32x16_bf16 v[2:17], v[234:237], v[186:189], v[2:17]
	v_mfma_f32_32x32x16_bf16 v[2:17], v[238:241], v[210:213], v[2:17]
	s_add_i32 s29, s29, 1
	s_add_u32 s28, s28, 19008
	s_cmp_eq_u32 s29, 4
	s_cselect_b32 s28, 0x90, s28
	s_cmp_eq_u32 s29, 7
	s_cbranch_scc0 .Lcl_loop
; __device__ __forceinline__ f32x16 mfma32(bf16x8 a, bf16x8 b, f32x16 c) { return __builtin_amdgcn_mfma_f32_32x32x16_bf16(a, b, c, 0, 0, 0); }
; __device__ __forceinline__ void compress_phase(lptr L, const Params& P, int l) {
;     ...
;         for (int p = 0; p < 32; ++p) {
;             int tok = tok0 + p; tok = tok > SEQ - 1 ? SEQ - 1 : tok;
;             const bf16_t* ar = Zb + (size_t)tok * ZLD; const bf16_t* br = B1 + p * 64;
; #pragma unroll
;             for (int s = 0; s < 4; ++s) acc = mfma32(*(const bf16x8*)(ar + 16 * s), *(const bf16x8*)(br + 16 * s), acc);
;         }
;         float peb = 0.f;
;         { const float* pp = (const float*)(ws + W_PEB) + src * 32 * 256 + 32 * wave + n;
; #pragma unroll 8
;           for (int q = 0; q < 32; ++q) peb += pp[q * 256]; }
	v_add_u32_e32 v140, s28, v141
	ds_read_b128 v[226:229], v140 offset:17408
	ds_read_b128 v[230:233], v140 offset:17440
	ds_read_b128 v[234:237], v140 offset:17472
	ds_read_b128 v[238:241], v140 offset:17504
	ds_read_b128 v[242:245], v142 offset:0
	ds_read_b128 v[246:249], v142 offset:32
	ds_read_b128 v[186:189], v142 offset:64
	ds_read_b128 v[210:213], v142 offset:96
	s_waitcnt vmcnt(8)
	ds_write_b128 v143, v[120:123] offset:0
	ds_write_b128 v143, v[124:127] offset:1152
	ds_write_b128 v143, v[128:131] offset:2304
	ds_write_b128 v143, v[132:135] offset:3456
	s_waitcnt lgkmcnt(4)
	v_mfma_f32_32x32x16_bf16 v[2:17], v[226:229], v[242:245], v[2:17]
	v_mfma_f32_32x32x16_bf16 v[2:17], v[230:233], v[246:249], v[2:17]
	v_mfma_f32_32x32x16_bf16 v[2:17], v[234:237], v[186:189], v[2:17]
	v_mfma_f32_32x32x16_bf16 v[2:17], v[238:241], v[210:213], v[2:17]
	ds_read_b128 v[226:229], v140 offset:22160
	ds_read_b128 v[230:233], v140 offset:22192
	ds_read_b128 v[234:237], v140 offset:22224
	ds_read_b128 v[238:241], v140 offset:22256
	ds_read_b128 v[242:245], v142 offset:0
	ds_read_b128 v[246:249], v142 offset:32
	ds_read_b128 v[186:189], v142 offset:64
	ds_read_b128 v[210:213], v142 offset:96
	s_waitcnt vmcnt(4)
	ds_write_b128 v143, v[170:173] offset:0
	ds_write_b128 v143, v[174:177] offset:1152
	ds_write_b128 v143, v[178:181] offset:2304
	ds_write_b128 v143, v[182:185] offset:3456
	s_waitcnt lgkmcnt(4)
	v_mfma_f32_32x32x16_bf16 v[2:17], v[226:229], v[242:245], v[2:17]
	v_mfma_f32_32x32x16_bf16 v[2:17], v[230:233], v[246:249], v[2:17]
	v_mfma_f32_32x32x16_bf16 v[2:17], v[234:237], v[186:189], v[2:17]
	v_mfma_f32_32x32x16_bf16 v[2:17], v[238:241], v[210:213], v[2:17]
	ds_read_b128 v[226:229], v140 offset:26912
	ds_read_b128 v[230:233], v140 offset:26944
	ds_read_b128 v[234:237], v140 offset:26976
	ds_read_b128 v[238:241], v140 offset:27008
	ds_read_b128 v[242:245], v142 offset:0
	ds_read_b128 v[246:249], v142 offset:32
	ds_read_b128 v[186:189], v142 offset:64
	ds_read_b128 v[210:213], v142 offset:96
	s_waitcnt vmcnt(0)
	ds_write_b128 v143, v[194:197] offset:0
	ds_write_b128 v143, v[198:201] offset:1152
	ds_write_b128 v143, v[202:205] offset:2304
	ds_write_b128 v143, v[206:209] offset:3456
	s_waitcnt lgkmcnt(4)
	v_mfma_f32_32x32x16_bf16 v[2:17], v[226:229], v[242:245], v[2:17]
	v_mfma_f32_32x32x16_bf16 v[2:17], v[230:233], v[246:249], v[2:17]
	v_mfma_f32_32x32x16_bf16 v[2:17], v[234:237], v[186:189], v[2:17]
	v_mfma_f32_32x32x16_bf16 v[2:17], v[238:241], v[210:213], v[2:17]
	ds_read_b128 v[226:229], v140 offset:31664
	ds_read_b128 v[230:233], v140 offset:31696
	ds_read_b128 v[234:237], v140 offset:31728
	ds_read_b128 v[238:241], v140 offset:31760
	ds_read_b128 v[242:245], v142 offset:0
	ds_read_b128 v[246:249], v142 offset:32
	ds_read_b128 v[186:189], v142 offset:64
	ds_read_b128 v[210:213], v142 offset:96
	s_waitcnt lgkmcnt(0)
	v_mfma_f32_32x32x16_bf16 v[2:17], v[226:229], v[242:245], v[2:17]
	v_mfma_f32_32x32x16_bf16 v[2:17], v[230:233], v[246:249], v[2:17]
	v_mfma_f32_32x32x16_bf16 v[2:17], v[234:237], v[186:189], v[2:17]
	v_mfma_f32_32x32x16_bf16 v[2:17], v[238:241], v[210:213], v[2:17]
	s_lshl_b32 s2, s0, 13
	s_ashr_i32 s3, s2, 31
	v_lshl_add_u64 v[62:63], s[2:3], 2, v[24:25]
	v_add_co_u32_e32 v88, vcc, 0x3590000, v62
	s_mov_b64 s[26:27], 0x1000
	s_nop 0
	v_addc_co_u32_e32 v89, vcc, 0, v63, vcc
	global_load_dword v98, v[88:89], off
	global_load_dword v99, v[88:89], off offset:1024
	global_load_dword v100, v[88:89], off offset:2048
	global_load_dword v101, v[88:89], off offset:3072
	v_lshl_add_u64 v[88:89], v[88:89], 0, s[26:27]
	global_load_dword v102, v[88:89], off
	global_load_dword v103, v[88:89], off offset:1024
	global_load_dword v104, v[88:89], off offset:2048
	global_load_dword v105, v[88:89], off offset:3072
	v_lshl_add_u64 v[88:89], v[88:89], 0, s[26:27]
	global_load_dword v106, v[88:89], off
	global_load_dword v107, v[88:89], off offset:1024
	global_load_dword v108, v[88:89], off offset:2048
	global_load_dword v109, v[88:89], off offset:3072
	v_lshl_add_u64 v[88:89], v[88:89], 0, s[26:27]
	global_load_dword v110, v[88:89], off
	global_load_dword v111, v[88:89], off offset:1024
	global_load_dword v112, v[88:89], off offset:2048
	global_load_dword v113, v[88:89], off offset:3072
	v_lshl_add_u64 v[88:89], v[88:89], 0, s[26:27]
	global_load_dword v114, v[88:89], off
	global_load_dword v115, v[88:89], off offset:1024
	global_load_dword v116, v[88:89], off offset:2048
	global_load_dword v117, v[88:89], off offset:3072
	v_lshl_add_u64 v[88:89], v[88:89], 0, s[26:27]
	global_load_dword v118, v[88:89], off
	global_load_dword v119, v[88:89], off offset:1024
	global_load_dword v120, v[88:89], off offset:2048
	global_load_dword v121, v[88:89], off offset:3072
	v_lshl_add_u64 v[88:89], v[88:89], 0, s[26:27]
	global_load_dword v122, v[88:89], off
	global_load_dword v123, v[88:89], off offset:1024
	global_load_dword v124, v[88:89], off offset:2048
	global_load_dword v125, v[88:89], off offset:3072
	v_lshl_add_u64 v[88:89], v[88:89], 0, s[26:27]
	global_load_dword v126, v[88:89], off
	global_load_dword v127, v[88:89], off offset:1024
	global_load_dword v128, v[88:89], off offset:2048
	global_load_dword v129, v[88:89], off offset:3072
	v_mov_b32_e32 v0, 0
	s_waitcnt vmcnt(0)
; __device__ __forceinline__ unsigned cvt_pk(float lo, float hi) { f32x2_t v = {lo, hi}; bf16x2_t b = __builtin_convertvector(v, bf16x2_t); return __builtin_bit_cast(unsigned, b); }
; __device__ __forceinline__ void compress_phase(lptr L, const Params& P, int l) {
;     ...
;         float peb = 0.f;
;         { const float* pp = (const float*)(ws + W_PEB) + src * 32 * 256 + 32 * wave + n;
; #pragma unroll 8
;           for (int q = 0; q < 32; ++q) peb += pp[q * 256]; }
; #pragma unroll
;         for (int r = 0; r < 16; ++r) {
;             const int row = 8 * (r >> 2) + 4 * hl + (r & 3);
;             const float hv = gelu_tanh(acc[r] + peb);
;             lds_st<bf16_t>(L + (row * HP + 32 * wave + n) * 2, (bf16_t)(cvt_pk(hv, 0.f) & 0xffffu));
;         }
	v_add_f32_e32 v0, v0, v98
	v_add_f32_e32 v0, v0, v99
	v_add_f32_e32 v0, v0, v100
	v_add_f32_e32 v0, v0, v101
	v_add_f32_e32 v0, v0, v102
	v_add_f32_e32 v0, v0, v103
	v_add_f32_e32 v0, v0, v104
	v_add_f32_e32 v0, v0, v105
	v_add_f32_e32 v0, v0, v106
	v_add_f32_e32 v0, v0, v107
	v_add_f32_e32 v0, v0, v108
	v_add_f32_e32 v0, v0, v109
	v_add_f32_e32 v0, v0, v110
	v_add_f32_e32 v0, v0, v111
	v_add_f32_e32 v0, v0, v112
	v_add_f32_e32 v0, v0, v113
	v_add_f32_e32 v0, v0, v114
	v_add_f32_e32 v0, v0, v115
	v_add_f32_e32 v0, v0, v116
	v_add_f32_e32 v0, v0, v117
	v_add_f32_e32 v0, v0, v118
	v_add_f32_e32 v0, v0, v119
	v_add_f32_e32 v0, v0, v120
	v_add_f32_e32 v0, v0, v121
	v_add_f32_e32 v0, v0, v122
	v_add_f32_e32 v0, v0, v123
	v_add_f32_e32 v0, v0, v124
	v_add_f32_e32 v0, v0, v125
	v_add_f32_e32 v0, v0, v126
	v_add_f32_e32 v0, v0, v127
	v_add_f32_e32 v0, v0, v128
	v_add_f32_e32 v0, v0, v129
	v_add_f32_e32 v2, v2, v0
	v_mul_f32_e32 v27, 0x3d372713, v2
	v_mul_f32_e32 v27, v2, v27
	v_fma_f32 v27, v2, v27, v2
	v_mul_f32_e32 v27, 0x3f4c422a, v27
	v_mul_f32_e32 v27, 0x4038aa3b, v27
	v_exp_f32_e32 v27, v27
	v_mul_f32_e32 v2, 0.5, v2
	v_add_f32_e32 v27, 1.0, v27
	v_rcp_f32_e32 v27, v27
	s_nop 0
	v_fma_f32 v27, v27, -2.0, 2.0
	v_mul_f32_e32 v2, v2, v27
	v_cvt_pk_bf16_f32 v2, v2, s0
	ds_write_b16 v69, v2
	v_add_f32_e32 v2, v3, v0
	v_mul_f32_e32 v3, 0x3d372713, v2
	v_mul_f32_e32 v3, v2, v3
	v_fma_f32 v3, v2, v3, v2
	v_mul_f32_e32 v3, 0x3f4c422a, v3
	v_mul_f32_e32 v3, 0x4038aa3b, v3
	v_exp_f32_e32 v3, v3
	v_mul_f32_e32 v2, 0.5, v2
	v_add_f32_e32 v3, 1.0, v3
	v_rcp_f32_e32 v3, v3
	s_nop 0
	v_fma_f32 v3, v3, -2.0, 2.0
	v_mul_f32_e32 v2, v2, v3
	v_cvt_pk_bf16_f32 v2, v2, s0
	ds_write_b16 v70, v2
	v_add_f32_e32 v2, v4, v0
	v_mul_f32_e32 v3, 0x3d372713, v2
	v_mul_f32_e32 v3, v2, v3
	v_fma_f32 v3, v2, v3, v2
	v_mul_f32_e32 v3, 0x3f4c422a, v3
	v_mul_f32_e32 v3, 0x4038aa3b, v3
	v_exp_f32_e32 v3, v3
	v_mul_f32_e32 v2, 0.5, v2
	v_add_f32_e32 v3, 1.0, v3
	v_rcp_f32_e32 v3, v3
	s_nop 0
	v_fma_f32 v3, v3, -2.0, 2.0
	v_mul_f32_e32 v2, v2, v3
	v_cvt_pk_bf16_f32 v2, v2, s0
	ds_write_b16 v71, v2
	v_add_f32_e32 v2, v5, v0
	v_mul_f32_e32 v3, 0x3d372713, v2
	v_mul_f32_e32 v3, v2, v3
	v_fma_f32 v3, v2, v3, v2
	v_mul_f32_e32 v3, 0x3f4c422a, v3
	v_mul_f32_e32 v3, 0x4038aa3b, v3
	v_exp_f32_e32 v3, v3
	v_mul_f32_e32 v2, 0.5, v2
	v_add_f32_e32 v3, 1.0, v3
	v_rcp_f32_e32 v3, v3
	s_nop 0
	v_fma_f32 v3, v3, -2.0, 2.0
	v_mul_f32_e32 v2, v2, v3
	v_cvt_pk_bf16_f32 v2, v2, s0
	ds_write_b16 v72, v2
	v_add_f32_e32 v2, v6, v0
	v_mul_f32_e32 v3, 0x3d372713, v2
	v_mul_f32_e32 v3, v2, v3
	v_fma_f32 v3, v2, v3, v2
	v_mul_f32_e32 v3, 0x3f4c422a, v3
	v_mul_f32_e32 v3, 0x4038aa3b, v3
	v_exp_f32_e32 v3, v3
	v_mul_f32_e32 v2, 0.5, v2
	v_add_f32_e32 v3, 1.0, v3
	v_rcp_f32_e32 v3, v3
	s_nop 0
	v_fma_f32 v3, v3, -2.0, 2.0
	v_mul_f32_e32 v2, v2, v3
	v_cvt_pk_bf16_f32 v2, v2, s0
	ds_write_b16 v73, v2
	v_add_f32_e32 v2, v7, v0
	v_mul_f32_e32 v3, 0x3d372713, v2
	v_mul_f32_e32 v3, v2, v3
	v_fma_f32 v3, v2, v3, v2
	v_mul_f32_e32 v3, 0x3f4c422a, v3
	v_mul_f32_e32 v3, 0x4038aa3b, v3
	v_exp_f32_e32 v3, v3
	v_mul_f32_e32 v2, 0.5, v2
	v_add_f32_e32 v3, 1.0, v3
	v_rcp_f32_e32 v3, v3
	s_nop 0
	v_fma_f32 v3, v3, -2.0, 2.0
	v_mul_f32_e32 v2, v2, v3
	v_cvt_pk_bf16_f32 v2, v2, s0
	ds_write_b16 v74, v2
	v_add_f32_e32 v2, v8, v0
	v_mul_f32_e32 v3, 0x3d372713, v2
	v_mul_f32_e32 v3, v2, v3
	v_fma_f32 v3, v2, v3, v2
	v_mul_f32_e32 v3, 0x3f4c422a, v3
	v_mul_f32_e32 v3, 0x4038aa3b, v3
	v_exp_f32_e32 v3, v3
	v_mul_f32_e32 v2, 0.5, v2
	v_add_f32_e32 v3, 1.0, v3
	v_rcp_f32_e32 v3, v3
	s_nop 0
	v_fma_f32 v3, v3, -2.0, 2.0
	v_mul_f32_e32 v2, v2, v3
	v_cvt_pk_bf16_f32 v2, v2, s0
	ds_write_b16 v75, v2
	v_add_f32_e32 v2, v9, v0
	v_mul_f32_e32 v3, 0x3d372713, v2
	v_mul_f32_e32 v3, v2, v3
	v_fma_f32 v3, v2, v3, v2
	v_mul_f32_e32 v3, 0x3f4c422a, v3
	v_mul_f32_e32 v3, 0x4038aa3b, v3
	v_exp_f32_e32 v3, v3
	v_mul_f32_e32 v2, 0.5, v2
	v_add_f32_e32 v3, 1.0, v3
	v_rcp_f32_e32 v3, v3
	s_nop 0
	v_fma_f32 v3, v3, -2.0, 2.0
	v_mul_f32_e32 v2, v2, v3
	v_cvt_pk_bf16_f32 v2, v2, s0
	ds_write_b16 v76, v2
	v_add_f32_e32 v2, v10, v0
	v_mul_f32_e32 v3, 0x3d372713, v2
	v_mul_f32_e32 v3, v2, v3
	v_fma_f32 v3, v2, v3, v2
	v_mul_f32_e32 v3, 0x3f4c422a, v3
	v_mul_f32_e32 v3, 0x4038aa3b, v3
	v_exp_f32_e32 v3, v3
	v_mul_f32_e32 v2, 0.5, v2
	v_add_f32_e32 v3, 1.0, v3
	v_rcp_f32_e32 v3, v3
	s_nop 0
	v_fma_f32 v3, v3, -2.0, 2.0
	v_mul_f32_e32 v2, v2, v3
	v_cvt_pk_bf16_f32 v2, v2, s0
	ds_write_b16 v77, v2
	v_add_f32_e32 v2, v11, v0
	v_mul_f32_e32 v3, 0x3d372713, v2
	v_mul_f32_e32 v3, v2, v3
	v_fma_f32 v3, v2, v3, v2
	v_mul_f32_e32 v3, 0x3f4c422a, v3
	v_mul_f32_e32 v3, 0x4038aa3b, v3
	v_exp_f32_e32 v3, v3
	v_mul_f32_e32 v2, 0.5, v2
	v_add_f32_e32 v3, 1.0, v3
	v_rcp_f32_e32 v3, v3
	s_nop 0
	v_fma_f32 v3, v3, -2.0, 2.0
	v_mul_f32_e32 v2, v2, v3
	v_cvt_pk_bf16_f32 v2, v2, s0
	ds_write_b16 v78, v2
	v_add_f32_e32 v2, v12, v0
	v_mul_f32_e32 v3, 0x3d372713, v2
	v_mul_f32_e32 v3, v2, v3
	v_fma_f32 v3, v2, v3, v2
	v_mul_f32_e32 v3, 0x3f4c422a, v3
	v_mul_f32_e32 v3, 0x4038aa3b, v3
	v_exp_f32_e32 v3, v3
	v_mul_f32_e32 v2, 0.5, v2
	v_add_f32_e32 v3, 1.0, v3
	v_rcp_f32_e32 v3, v3
	s_nop 0
	v_fma_f32 v3, v3, -2.0, 2.0
	v_mul_f32_e32 v2, v2, v3
	v_cvt_pk_bf16_f32 v2, v2, s0
	ds_write_b16 v79, v2
	v_add_f32_e32 v2, v13, v0
	v_mul_f32_e32 v3, 0x3d372713, v2
	v_mul_f32_e32 v3, v2, v3
	v_fma_f32 v3, v2, v3, v2
	v_mul_f32_e32 v3, 0x3f4c422a, v3
	v_mul_f32_e32 v3, 0x4038aa3b, v3
	v_exp_f32_e32 v3, v3
	v_mul_f32_e32 v2, 0.5, v2
	v_add_f32_e32 v3, 1.0, v3
	v_rcp_f32_e32 v3, v3
	s_nop 0
	v_fma_f32 v3, v3, -2.0, 2.0
	v_mul_f32_e32 v2, v2, v3
	v_cvt_pk_bf16_f32 v2, v2, s0
	ds_write_b16 v80, v2
; __device__ __forceinline__ unsigned cvt_pk(float lo, float hi) { f32x2_t v = {lo, hi}; bf16x2_t b = __builtin_convertvector(v, bf16x2_t); return __builtin_bit_cast(unsigned, b); }
; __device__ __forceinline__ void compress_phase(lptr L, const Params& P, int l) {
;     ...
;         for (int r = 0; r < 16; ++r) {
;             const int row = 8 * (r >> 2) + 4 * hl + (r & 3);
;             const float hv = gelu_tanh(acc[r] + peb);
;             lds_st<bf16_t>(L + (row * HP + 32 * wave + n) * 2, (bf16_t)(cvt_pk(hv, 0.f) & 0xffffu));
;         }
;         __syncthreads();
;         if (wave < 2) {
	v_add_f32_e32 v2, v14, v0
	v_mul_f32_e32 v3, 0x3d372713, v2
	v_mul_f32_e32 v3, v2, v3
	v_fma_f32 v3, v2, v3, v2
	v_mul_f32_e32 v3, 0x3f4c422a, v3
	v_mul_f32_e32 v3, 0x4038aa3b, v3
	v_exp_f32_e32 v3, v3
	v_mul_f32_e32 v2, 0.5, v2
	v_add_f32_e32 v3, 1.0, v3
	v_rcp_f32_e32 v3, v3
	s_nop 0
	v_fma_f32 v3, v3, -2.0, 2.0
	v_mul_f32_e32 v2, v2, v3
	v_cvt_pk_bf16_f32 v2, v2, s0
	ds_write_b16 v81, v2
	v_add_f32_e32 v2, v15, v0
	v_mul_f32_e32 v3, 0x3d372713, v2
	v_mul_f32_e32 v3, v2, v3
	v_fma_f32 v3, v2, v3, v2
	v_mul_f32_e32 v3, 0x3f4c422a, v3
	v_mul_f32_e32 v3, 0x4038aa3b, v3
	v_exp_f32_e32 v3, v3
	v_mul_f32_e32 v2, 0.5, v2
	v_add_f32_e32 v3, 1.0, v3
	v_rcp_f32_e32 v3, v3
	s_nop 0
	v_fma_f32 v3, v3, -2.0, 2.0
	v_mul_f32_e32 v2, v2, v3
	v_cvt_pk_bf16_f32 v2, v2, s0
	ds_write_b16 v82, v2
	v_add_f32_e32 v2, v16, v0
	v_mul_f32_e32 v3, 0x3d372713, v2
	v_mul_f32_e32 v3, v2, v3
	v_fma_f32 v3, v2, v3, v2
	v_mul_f32_e32 v3, 0x3f4c422a, v3
	v_mul_f32_e32 v3, 0x4038aa3b, v3
	v_exp_f32_e32 v3, v3
	v_mul_f32_e32 v2, 0.5, v2
	v_add_f32_e32 v0, v17, v0
	v_add_f32_e32 v3, 1.0, v3
	v_rcp_f32_e32 v3, v3
	s_nop 0
	v_fma_f32 v3, v3, -2.0, 2.0
	v_mul_f32_e32 v2, v2, v3
	v_cvt_pk_bf16_f32 v2, v2, s0
	ds_write_b16 v83, v2
	v_mul_f32_e32 v2, 0x3d372713, v0
	v_mul_f32_e32 v2, v0, v2
	v_fma_f32 v2, v0, v2, v0
	v_mul_f32_e32 v2, 0x3f4c422a, v2
	v_mul_f32_e32 v2, 0x4038aa3b, v2
	v_exp_f32_e32 v2, v2
	v_mul_f32_e32 v0, 0.5, v0
	v_add_f32_e32 v2, 1.0, v2
	v_rcp_f32_e32 v2, v2
	s_nop 0
	v_fma_f32 v2, v2, -2.0, 2.0
	v_mul_f32_e32 v0, v0, v2
	v_cvt_pk_bf16_f32 v0, v0, s0
	ds_write_b16 v85, v0
	s_waitcnt lgkmcnt(0)
	s_barrier
	s_and_saveexec_b64 s[2:3], s[38:39]
	s_cbranch_execz .LBB0_201
; __device__ __forceinline__ unsigned cvt_pk(float lo, float hi) { f32x2_t v = {lo, hi}; bf16x2_t b = __builtin_convertvector(v, bf16x2_t); return __builtin_bit_cast(unsigned, b); }
; __device__ __forceinline__ f32x16 mfma32(bf16x8 a, bf16x8 b, f32x16 c) { return __builtin_amdgcn_mfma_f32_32x32x16_bf16(a, b, c, 0, 0, 0); }
; __device__ __forceinline__ void compress_phase(lptr L, const Params& P, int l) {
;     ...
;         if (wave < 2) {
;             const bf16_t* B2 = (const bf16_t*)(ws + W_C2) + (size_t)src * 64 * 256 + (size_t)(32 * wave + n) * 256 + 8 * hl;
;             f32x16 a2 = {};
; #pragma unroll
;             for (int s = 0; s < 16; ++s) a2 = mfma32(lds_ld<bf16x8>(L + (n * HP + 16 * s + 8 * hl) * 2), *(const bf16x8*)(B2 + 16 * s), a2);
;             bf16_t* out = (bf16_t*)(ws + WS_KC) + ((size_t)(src * 16 + bg) * 256 + i0) * 64 + 32 * wave + n;
; #pragma unroll
;             for (int r = 0; r < 16; ++r) {
;                 const int row = 8 * (r >> 2) + 4 * hl + (r & 3);
;                 const float v = (i0 + row < 255) ? a2[r] : 0.f;
;                 out[(size_t)row * 64] = (bf16_t)(cvt_pk(v, 0.f) & 0xffffu);
;             }
	s_lshl_b64 s[26:27], s[0:1], 15
	v_lshl_add_u64 v[92:93], v[20:21], 0, s[26:27]
	global_load_dwordx4 v[2:5], v[92:93], off
	ds_read_b128 v[6:9], v86
	ds_read_b128 v[62:65], v86 offset:32
	global_load_dwordx4 v[88:91], v[92:93], off offset:32
	s_lshl_b32 s0, s0, 4
	s_or_b32 s0, s0, s7
	s_lshl_b32 s10, s6, 5
	s_ashr_i32 s1, s0, 31
	s_and_b32 s10, s10, 0xe0
	s_lshl_b64 s[0:1], s[0:1], 15
	v_readlane_b32 s7, v253, 35
	s_add_u32 s0, s7, s0
	v_readlane_b32 s7, v253, 36
	s_addc_u32 s1, s7, s1
	s_lshl_b32 s7, s10, 7
	s_add_u32 s0, s0, s7
	s_addc_u32 s1, s1, 0
	v_mov_b32_e32 v29, v1
	v_mov_b32_e32 v31, v1
	v_mov_b32_e32 v33, v1
	v_mov_b32_e32 v35, v1
	v_mov_b32_e32 v37, v1
	v_mov_b32_e32 v39, v1
	v_mov_b32_e32 v41, v1
	v_mov_b32_e32 v43, v1
	v_mov_b32_e32 v45, v1
	v_mov_b32_e32 v47, v1
	v_mov_b32_e32 v49, v1
	v_mov_b32_e32 v51, v1
	v_mov_b32_e32 v53, v1
	v_mov_b32_e32 v55, v1
	v_mov_b32_e32 v57, v1
	v_mov_b32_e32 v59, v1
	v_mov_b32_e32 v61, v1
	s_waitcnt vmcnt(1) lgkmcnt(1)
	v_mfma_f32_32x32x16_bf16 v[2:17], v[6:9], v[2:5], 0
	s_waitcnt vmcnt(0) lgkmcnt(0)
	v_mfma_f32_32x32x16_bf16 v[2:17], v[62:65], v[88:91], v[2:17]
	global_load_dwordx4 v[88:91], v[92:93], off offset:64
	ds_read_b128 v[62:65], v86 offset:64
	s_waitcnt vmcnt(0) lgkmcnt(0)
	v_mfma_f32_32x32x16_bf16 v[2:17], v[62:65], v[88:91], v[2:17]
	global_load_dwordx4 v[88:91], v[92:93], off offset:96
	ds_read_b128 v[62:65], v86 offset:96
	s_waitcnt vmcnt(0) lgkmcnt(0)
	v_mfma_f32_32x32x16_bf16 v[2:17], v[62:65], v[88:91], v[2:17]
	global_load_dwordx4 v[88:91], v[92:93], off offset:128
	ds_read_b128 v[62:65], v86 offset:128
	s_waitcnt vmcnt(0) lgkmcnt(0)
	v_mfma_f32_32x32x16_bf16 v[2:17], v[62:65], v[88:91], v[2:17]
	global_load_dwordx4 v[88:91], v[92:93], off offset:160
	ds_read_b128 v[62:65], v86 offset:160
	s_waitcnt vmcnt(0) lgkmcnt(0)
	v_mfma_f32_32x32x16_bf16 v[2:17], v[62:65], v[88:91], v[2:17]
	global_load_dwordx4 v[88:91], v[92:93], off offset:192
	ds_read_b128 v[62:65], v86 offset:192
	s_waitcnt vmcnt(0) lgkmcnt(0)
	v_mfma_f32_32x32x16_bf16 v[2:17], v[62:65], v[88:91], v[2:17]
	global_load_dwordx4 v[88:91], v[92:93], off offset:224
	ds_read_b128 v[62:65], v86 offset:224
	s_waitcnt vmcnt(0) lgkmcnt(0)
	v_mfma_f32_32x32x16_bf16 v[2:17], v[62:65], v[88:91], v[2:17]
	global_load_dwordx4 v[88:91], v[92:93], off offset:256
	ds_read_b128 v[62:65], v86 offset:256
	s_waitcnt vmcnt(0) lgkmcnt(0)
	v_mfma_f32_32x32x16_bf16 v[2:17], v[62:65], v[88:91], v[2:17]
	global_load_dwordx4 v[88:91], v[92:93], off offset:288
	ds_read_b128 v[62:65], v86 offset:288
	s_waitcnt vmcnt(0) lgkmcnt(0)
	v_mfma_f32_32x32x16_bf16 v[2:17], v[62:65], v[88:91], v[2:17]
	global_load_dwordx4 v[88:91], v[92:93], off offset:320
	ds_read_b128 v[62:65], v86 offset:320
	s_waitcnt vmcnt(0) lgkmcnt(0)
	v_mfma_f32_32x32x16_bf16 v[2:17], v[62:65], v[88:91], v[2:17]
	global_load_dwordx4 v[88:91], v[92:93], off offset:352
	ds_read_b128 v[62:65], v86 offset:352
	s_waitcnt vmcnt(0) lgkmcnt(0)
	v_mfma_f32_32x32x16_bf16 v[2:17], v[62:65], v[88:91], v[2:17]
	global_load_dwordx4 v[88:91], v[92:93], off offset:384
	ds_read_b128 v[62:65], v86 offset:384
	s_waitcnt vmcnt(0) lgkmcnt(0)
	v_mfma_f32_32x32x16_bf16 v[2:17], v[62:65], v[88:91], v[2:17]
	global_load_dwordx4 v[88:91], v[92:93], off offset:416
	ds_read_b128 v[62:65], v86 offset:416
	s_waitcnt vmcnt(0) lgkmcnt(0)
	v_mfma_f32_32x32x16_bf16 v[2:17], v[62:65], v[88:91], v[2:17]
	global_load_dwordx4 v[88:91], v[92:93], off offset:448
	ds_read_b128 v[62:65], v86 offset:448
	s_waitcnt vmcnt(0) lgkmcnt(0)
	v_mfma_f32_32x32x16_bf16 v[2:17], v[62:65], v[88:91], v[2:17]
	global_load_dwordx4 v[88:91], v[92:93], off offset:480
	ds_read_b128 v[62:65], v86 offset:480
	s_waitcnt vmcnt(0) lgkmcnt(0)
	v_mfma_f32_32x32x16_bf16 v[2:17], v[62:65], v[88:91], v[2:17]
	v_lshl_add_u64 v[62:63], v[18:19], 1, s[0:1]
	v_lshl_add_u64 v[62:63], v[62:63], 0, v[28:29]
	v_lshl_add_u64 v[64:65], v[62:63], 0, v[30:31]
	s_nop 8
	v_cvt_pk_bf16_f32 v0, v2, s0
	global_store_short v[64:65], v0, off
	v_cvt_pk_bf16_f32 v0, v3, s0
	v_lshl_add_u64 v[2:3], v[62:63], 0, v[32:33]
	global_store_short v[2:3], v0, off
	v_cvt_pk_bf16_f32 v0, v4, s0
	v_lshl_add_u64 v[2:3], v[62:63], 0, v[34:35]
	global_store_short v[2:3], v0, off
	v_cvt_pk_bf16_f32 v0, v5, s0
	v_lshl_add_u64 v[2:3], v[62:63], 0, v[36:37]
	global_store_short v[2:3], v0, off
	v_cvt_pk_bf16_f32 v0, v6, s0
	v_lshl_add_u64 v[2:3], v[62:63], 0, v[38:39]
	global_store_short v[2:3], v0, off
	v_cvt_pk_bf16_f32 v0, v7, s0
	v_lshl_add_u64 v[2:3], v[62:63], 0, v[40:41]
	global_store_short v[2:3], v0, off
	v_cvt_pk_bf16_f32 v0, v8, s0
	v_lshl_add_u64 v[2:3], v[62:63], 0, v[42:43]
	global_store_short v[2:3], v0, off
	v_cvt_pk_bf16_f32 v0, v9, s0
	v_lshl_add_u64 v[2:3], v[62:63], 0, v[44:45]
	global_store_short v[2:3], v0, off
	v_cvt_pk_bf16_f32 v0, v10, s0
	v_lshl_add_u64 v[2:3], v[62:63], 0, v[46:47]
	global_store_short v[2:3], v0, off
	v_cvt_pk_bf16_f32 v0, v11, s0
	v_lshl_add_u64 v[2:3], v[62:63], 0, v[48:49]
	global_store_short v[2:3], v0, off
	v_cvt_pk_bf16_f32 v0, v12, s0
	v_lshl_add_u64 v[2:3], v[62:63], 0, v[50:51]
	global_store_short v[2:3], v0, off
	v_cvt_pk_bf16_f32 v0, v13, s0
	v_lshl_add_u64 v[2:3], v[62:63], 0, v[52:53]
	global_store_short v[2:3], v0, off
	v_cvt_pk_bf16_f32 v0, v14, s0
	v_lshl_add_u64 v[2:3], v[62:63], 0, v[54:55]
	global_store_short v[2:3], v0, off
	v_cvt_pk_bf16_f32 v0, v15, s0
	v_lshl_add_u64 v[2:3], v[62:63], 0, v[56:57]
	global_store_short v[2:3], v0, off
	v_cvt_pk_bf16_f32 v0, v16, s0
	v_lshl_add_u64 v[2:3], v[62:63], 0, v[58:59]
	global_store_short v[2:3], v0, off
	v_or_b32_e32 v0, s10, v84
	v_cvt_pk_bf16_f32 v2, v17, s0
	s_movk_i32 s0, 0xff
	v_cmp_ne_u32_e32 vcc, s0, v0
	s_nop 1
	v_cndmask_b32_e32 v0, 0, v2, vcc
	v_lshl_add_u64 v[2:3], v[62:63], 0, v[60:61]
	global_store_short v[2:3], v0, off
	s_branch .LBB0_201

; __device__ __forceinline__ float ex2(float x) { return __builtin_amdgcn_exp2f(x); }
; __device__ __forceinline__ float half_other(float x, int hl) { auto rr = __builtin_amdgcn_permlane32_swap(__float_as_uint(x), __float_as_uint(x), false, false); return hl ? __uint_as_float(rr[0]) : __uint_as_float(rr[1]); }
; template <int MODE> ...
;     ...
;             for (int r = 0; r < 16; ++r) { s0[r] = ex2(s0[r]) * linv; s1[r] = ex2(s1[r]) * linv; }
;             float quad[8], last[8], recv[8];
; #pragma unroll
;             for (int a = 0; a < 4; ++a) {
;                 quad[a] = (s0[4 * a] + s0[4 * a + 1]) + (s0[4 * a + 2] + s0[4 * a + 3]); last[a] = s0[4 * a + 3];
;                 quad[4 + a] = (s1[4 * a] + s1[4 * a + 1]) + (s1[4 * a + 2] + s1[4 * a + 3]); last[4 + a] = s1[4 * a + 3];
;             }
; #pragma unroll
;             for (int i = 0; i < 8; ++i) recv[i] = half_other(last[i], hl);
; #pragma unroll
;             for (int i = 0; i < 8; ++i) {
;                 const float prev = (i > 0) ? recv[i > 0 ? i - 1 : 0] : carry;
;                 float v = quad[i] + (hl ? recv[i] : prev);
;                 v += __shfl_xor(v, 1); v += __shfl_xor(v, 2);
;                 if ((n & 3) == 0) lds_st<float>(L + score_ofs + (16 * kt + 2 * i + hl) * 4, v);
;             }
;             carry = recv[7];
.LBB0_251:
	s_or_b64 exec, exec, s[0:1]
	s_nop 5
	v_exp_f32_e32 v50, v66
	v_exp_f32_e32 v51, v67
	v_exp_f32_e32 v54, v84
	v_exp_f32_e32 v55, v85
	v_exp_f32_e32 v52, v68
	v_pk_mul_f32 v[62:63], v[194:195], v[50:51]
	v_exp_f32_e32 v50, v72
	v_exp_f32_e32 v51, v73
	v_exp_f32_e32 v53, v69
	v_pk_mul_f32 v[56:57], v[194:195], v[54:55]
	v_exp_f32_e32 v54, v80
	v_pk_mul_f32 v[66:67], v[194:195], v[50:51]
	v_exp_f32_e32 v50, v76
	v_exp_f32_e32 v51, v77
	v_exp_f32_e32 v72, v96
	v_exp_f32_e32 v55, v81
	v_exp_f32_e32 v73, v97
	v_pk_mul_f32 v[64:65], v[194:195], v[52:53]
	v_pk_mul_f32 v[60:61], v[194:195], v[50:51]
	v_add_f32_e32 v50, v64, v65
	v_add_f32_e32 v51, v62, v63
	v_pk_mul_f32 v[68:69], v[194:195], v[54:55]
	v_pk_mul_f32 v[54:55], v[194:195], v[72:73]
	v_add_f32_e32 v51, v51, v50
	v_mov_b32_e32 v50, v65
	v_mov_b32_e32 v72, v65
	s_nop 1
	v_permlane32_swap_b32_e32 v50, v72
	v_exp_f32_e32 v53, v93
	v_cndmask_b32_e64 v93, v50, v72, s[38:39]
	v_cndmask_b32_e64 v80, v93, v217, s[38:39]
	v_add_f32_e32 v81, v51, v80
	s_nop 1
	v_mov_b32_dpp v84, v81 quad_perm:[1,0,3,2] row_mask:0xf bank_mask:0xf
	v_exp_f32_e32 v58, v88
	v_exp_f32_e32 v59, v89
	v_exp_f32_e32 v52, v92
	v_mov_b32_e32 v96, v67
	s_waitcnt lgkmcnt(0)
	v_add_f32_e32 v98, v81, v84
	s_nop 1
	v_mov_b32_dpp v99, v98 quad_perm:[2,3,0,1] row_mask:0xf bank_mask:0xf
	v_pk_mul_f32 v[58:59], v[194:195], v[58:59]
	v_pk_mul_f32 v[52:53], v[194:195], v[52:53]
	v_mov_b32_e32 v97, v67
	v_mov_b32_e32 v72, v61
	v_mov_b32_e32 v73, v61
	v_mov_b32_e32 v89, v69
	v_mov_b32_e32 v92, v69
	v_mov_b32_e32 v76, v57
	v_mov_b32_e32 v77, v57
	v_mov_b32_e32 v85, v59
	v_mov_b32_e32 v88, v59
	v_mov_b32_e32 v50, v53
	v_mov_b32_e32 v51, v53
	v_mov_b32_e32 v80, v55
	v_mov_b32_e32 v81, v55
	v_permlane32_swap_b32_e32 v96, v97
	v_permlane32_swap_b32_e32 v72, v73
	v_permlane32_swap_b32_e32 v89, v92
	v_permlane32_swap_b32_e32 v76, v77
	v_permlane32_swap_b32_e32 v85, v88
	v_permlane32_swap_b32_e32 v50, v51
	v_permlane32_swap_b32_e32 v80, v81
	v_lshl_add_u32 v84, s6, 6, v247
	s_and_saveexec_b64 s[0:1], s[40:41]
	s_cbranch_execz .LBB0_253
	s_waitcnt lgkmcnt(0)
	v_add_f32_e32 v98, v98, v99
	ds_write_b32 v84, v98 offset:43520
.LBB0_253:
	s_or_b64 exec, exec, s[0:1]
	v_exp_f32_e32 v70, v70
	v_exp_f32_e32 v71, v71
	v_add_f32_e32 v98, v66, v67
	v_cndmask_b32_e64 v96, v96, v97, s[38:39]
	v_cndmask_b32_e64 v93, v96, v93, s[38:39]
	v_pk_mul_f32 v[70:71], v[194:195], v[70:71]
	s_nop 0
	v_add_f32_e32 v97, v70, v71
	v_add_f32_e32 v97, v97, v98
	v_add_f32_e32 v93, v97, v93
	s_nop 1
	v_mov_b32_dpp v97, v93 quad_perm:[1,0,3,2] row_mask:0xf bank_mask:0xf
	s_waitcnt lgkmcnt(0)
	v_add_f32_e32 v93, v93, v97
	s_nop 1
	v_mov_b32_dpp v97, v93 quad_perm:[2,3,0,1] row_mask:0xf bank_mask:0xf
	s_and_saveexec_b64 s[0:1], s[40:41]
	s_cbranch_execz .LBB0_255
	s_waitcnt lgkmcnt(0)
	v_add_f32_e32 v93, v93, v97
	ds_write_b32 v84, v93 offset:43528
.LBB0_255:
	s_or_b64 exec, exec, s[0:1]
	v_exp_f32_e32 v74, v74
	v_exp_f32_e32 v75, v75
	v_cndmask_b32_e64 v93, v72, v73, s[38:39]
	s_waitcnt lgkmcnt(0)
	v_add_f32_e32 v97, v60, v61
	v_pk_mul_f32 v[72:73], v[194:195], v[74:75]
	s_nop 0
	v_add_f32_e32 v74, v72, v73
	v_add_f32_e32 v74, v74, v97
	v_cndmask_b32_e64 v75, v93, v96, s[38:39]
	v_add_f32_e32 v74, v74, v75
	s_nop 1
	v_mov_b32_dpp v75, v74 quad_perm:[1,0,3,2] row_mask:0xf bank_mask:0xf
	s_waitcnt lgkmcnt(0)
	v_add_f32_e32 v74, v74, v75
	s_nop 1
	v_mov_b32_dpp v75, v74 quad_perm:[2,3,0,1] row_mask:0xf bank_mask:0xf
	s_and_saveexec_b64 s[0:1], s[40:41]
	s_cbranch_execz .LBB0_257
	s_waitcnt lgkmcnt(0)
	v_add_f32_e32 v74, v74, v75
	ds_write_b32 v84, v74 offset:43536
; __device__ __forceinline__ float ex2(float x) { return __builtin_amdgcn_exp2f(x); }
; __device__ __forceinline__ float half_other(float x, int hl) { auto rr = __builtin_amdgcn_permlane32_swap(__float_as_uint(x), __float_as_uint(x), false, false); return hl ? __uint_as_float(rr[0]) : __uint_as_float(rr[1]); }
; template <int MODE> ...
;     ...
;         } else {
; #pragma unroll
;             for (int r = 0; r < 16; ++r) { s0[r] = ex2(s0[r]) * linv; s1[r] = ex2(s1[r]) * linv; }
;             float quad[8], last[8], recv[8];
; #pragma unroll
;             for (int a = 0; a < 4; ++a) {
;                 quad[a] = (s0[4 * a] + s0[4 * a + 1]) + (s0[4 * a + 2] + s0[4 * a + 3]); last[a] = s0[4 * a + 3];
;                 quad[4 + a] = (s1[4 * a] + s1[4 * a + 1]) + (s1[4 * a + 2] + s1[4 * a + 3]); last[4 + a] = s1[4 * a + 3];
;             }
; #pragma unroll
;             for (int i = 0; i < 8; ++i) recv[i] = half_other(last[i], hl);
; #pragma unroll
;             for (int i = 0; i < 8; ++i) {
;                 const float prev = (i > 0) ? recv[i > 0 ? i - 1 : 0] : carry;
;                 float v = quad[i] + (hl ? recv[i] : prev);
;                 v += __shfl_xor(v, 1); v += __shfl_xor(v, 2);
;                 if ((n & 3) == 0) lds_st<float>(L + score_ofs + (16 * kt + 2 * i + hl) * 4, v);
;             }
;             carry = recv[7];
;         }
.LBB0_257:
	s_or_b64 exec, exec, s[0:1]
	v_exp_f32_e32 v74, v78
	s_waitcnt lgkmcnt(0)
	v_exp_f32_e32 v75, v79
	v_add_f32_e32 v79, v68, v69
	v_cndmask_b32_e64 v78, v89, v92, s[38:39]
	v_pk_mul_f32 v[74:75], v[194:195], v[74:75]
	s_nop 0
	v_add_f32_e32 v89, v74, v75
	v_add_f32_e32 v79, v89, v79
	v_cndmask_b32_e64 v89, v78, v93, s[38:39]
	v_add_f32_e32 v79, v79, v89
	s_nop 1
	v_mov_b32_dpp v89, v79 quad_perm:[1,0,3,2] row_mask:0xf bank_mask:0xf
	s_waitcnt lgkmcnt(0)
	v_add_f32_e32 v79, v79, v89
	s_nop 1
	v_mov_b32_dpp v89, v79 quad_perm:[2,3,0,1] row_mask:0xf bank_mask:0xf
	s_and_saveexec_b64 s[0:1], s[40:41]
	s_cbranch_execz .LBB0_259
	s_waitcnt lgkmcnt(0)
	v_add_f32_e32 v79, v79, v89
	ds_write_b32 v84, v79 offset:43544
.LBB0_259:
	s_or_b64 exec, exec, s[0:1]
	v_exp_f32_e32 v92, v82
	v_exp_f32_e32 v93, v83
	v_cndmask_b32_e64 v82, v76, v77, s[38:39]
	v_add_f32_e32 v79, v56, v57
	v_cndmask_b32_e64 v78, v82, v78, s[38:39]
	v_pk_mul_f32 v[76:77], v[194:195], v[92:93]
	s_nop 0
	v_add_f32_e32 v83, v76, v77
	v_add_f32_e32 v79, v83, v79
	v_add_f32_e32 v78, v79, v78
	s_nop 1
	v_mov_b32_dpp v79, v78 quad_perm:[1,0,3,2] row_mask:0xf bank_mask:0xf
	s_waitcnt lgkmcnt(0)
	v_add_f32_e32 v78, v78, v79
	s_nop 1
	v_mov_b32_dpp v79, v78 quad_perm:[2,3,0,1] row_mask:0xf bank_mask:0xf
	s_and_saveexec_b64 s[0:1], s[40:41]
	s_cbranch_execz .LBB0_261
	s_waitcnt lgkmcnt(0)
	v_add_f32_e32 v78, v78, v79
	ds_write_b32 v84, v78 offset:43552
.LBB0_261:
	s_or_b64 exec, exec, s[0:1]
	v_exp_f32_e32 v78, v86
	s_waitcnt lgkmcnt(0)
	v_exp_f32_e32 v79, v87
	v_add_f32_e32 v86, v58, v59
	v_cndmask_b32_e64 v83, v85, v88, s[38:39]
	v_cndmask_b32_e64 v82, v83, v82, s[38:39]
	v_pk_mul_f32 v[78:79], v[194:195], v[78:79]
	s_nop 0
	v_add_f32_e32 v85, v78, v79
	v_add_f32_e32 v85, v85, v86
	v_add_f32_e32 v82, v85, v82
	s_nop 1
	v_mov_b32_dpp v85, v82 quad_perm:[1,0,3,2] row_mask:0xf bank_mask:0xf
	s_waitcnt lgkmcnt(0)
	v_add_f32_e32 v82, v82, v85
	s_nop 1
	v_mov_b32_dpp v85, v82 quad_perm:[2,3,0,1] row_mask:0xf bank_mask:0xf
	s_and_saveexec_b64 s[0:1], s[40:41]
	s_cbranch_execz .LBB0_263
	s_waitcnt lgkmcnt(0)
	v_add_f32_e32 v82, v82, v85
	ds_write_b32 v84, v82 offset:43560
.LBB0_263:
	s_or_b64 exec, exec, s[0:1]
	v_exp_f32_e32 v86, v90
	v_exp_f32_e32 v87, v91
	v_cndmask_b32_e64 v82, v50, v51, s[38:39]
	s_waitcnt lgkmcnt(0)
	v_add_f32_e32 v85, v52, v53
	v_cndmask_b32_e64 v83, v82, v83, s[38:39]
	v_pk_mul_f32 v[50:51], v[194:195], v[86:87]
	s_nop 0
	v_add_f32_e32 v86, v50, v51
	v_add_f32_e32 v85, v86, v85
	v_add_f32_e32 v83, v85, v83
	s_nop 1
	v_mov_b32_dpp v85, v83 quad_perm:[1,0,3,2] row_mask:0xf bank_mask:0xf
	s_waitcnt lgkmcnt(0)
	v_add_f32_e32 v83, v83, v85
	s_nop 1
	v_mov_b32_dpp v85, v83 quad_perm:[2,3,0,1] row_mask:0xf bank_mask:0xf
	s_and_saveexec_b64 s[0:1], s[40:41]
	s_cbranch_execz .LBB0_265
	s_waitcnt lgkmcnt(0)
	v_add_f32_e32 v83, v83, v85
	ds_write_b32 v84, v83 offset:43568
.LBB0_265:
	s_or_b64 exec, exec, s[0:1]
	v_exp_f32_e32 v86, v94
	v_exp_f32_e32 v87, v95
	v_cndmask_b32_e64 v217, v80, v81, s[38:39]
	v_add_f32_e32 v83, v54, v55
	v_cndmask_b32_e64 v82, v217, v82, s[38:39]
	v_pk_mul_f32 v[80:81], v[194:195], v[86:87]
	s_waitcnt lgkmcnt(0)
	v_add_f32_e32 v85, v80, v81
	v_add_f32_e32 v83, v85, v83
	v_add_f32_e32 v82, v83, v82
	s_nop 1
	v_mov_b32_dpp v83, v82 quad_perm:[1,0,3,2] row_mask:0xf bank_mask:0xf
	s_waitcnt lgkmcnt(0)
	v_add_f32_e32 v82, v82, v83
	s_nop 1
	v_mov_b32_dpp v83, v82 quad_perm:[2,3,0,1] row_mask:0xf bank_mask:0xf
	s_and_saveexec_b64 s[0:1], s[40:41]
	s_cbranch_execz .LBB0_267
	s_waitcnt lgkmcnt(0)
	v_add_f32_e32 v82, v82, v83
	ds_write_b32 v84, v82 offset:43576

; __device__ __forceinline__ float ex2(float x) { return __builtin_amdgcn_exp2f(x); }
; __device__ __forceinline__ float half_other(float x, int hl) { auto rr = __builtin_amdgcn_permlane32_swap(__float_as_uint(x), __float_as_uint(x), false, false); return hl ? __uint_as_float(rr[0]) : __uint_as_float(rr[1]); }
; template <int MODE> ...
;     ...
;         } else {
; #pragma unroll
;             for (int r = 0; r < 16; ++r) { s0[r] = ex2(s0[r]) * linv; s1[r] = ex2(s1[r]) * linv; }
;             float quad[8], last[8], recv[8];
; #pragma unroll
;             for (int a = 0; a < 4; ++a) {
;                 quad[a] = (s0[4 * a] + s0[4 * a + 1]) + (s0[4 * a + 2] + s0[4 * a + 3]); last[a] = s0[4 * a + 3];
;                 quad[4 + a] = (s1[4 * a] + s1[4 * a + 1]) + (s1[4 * a + 2] + s1[4 * a + 3]); last[4 + a] = s1[4 * a + 3];
;             }
; #pragma unroll
;             for (int i = 0; i < 8; ++i) recv[i] = half_other(last[i], hl);
; #pragma unroll
;             for (int i = 0; i < 8; ++i) {
;                 const float prev = (i > 0) ? recv[i > 0 ? i - 1 : 0] : carry;
;                 float v = quad[i] + (hl ? recv[i] : prev);
;                 v += __shfl_xor(v, 1); v += __shfl_xor(v, 2);
;                 if ((n & 3) == 0) lds_st<float>(L + score_ofs + (16 * kt + 2 * i + hl) * 4, v);
;             }
;             carry = recv[7];
;         }
.LBB0_276:
	s_or_b64 exec, exec, s[0:1]
	s_nop 5
	v_exp_f32_e32 v50, v66
	v_exp_f32_e32 v51, v67
	v_exp_f32_e32 v54, v84
	v_exp_f32_e32 v55, v85
	v_exp_f32_e32 v52, v68
	v_pk_mul_f32 v[58:59], v[194:195], v[50:51]
	v_exp_f32_e32 v50, v72
	v_exp_f32_e32 v51, v73
	v_exp_f32_e32 v53, v69
	v_pk_mul_f32 v[56:57], v[194:195], v[54:55]
	v_exp_f32_e32 v54, v80
	v_pk_mul_f32 v[62:63], v[194:195], v[50:51]
	v_exp_f32_e32 v50, v76
	v_exp_f32_e32 v51, v77
	v_exp_f32_e32 v72, v96
	v_exp_f32_e32 v55, v81
	v_exp_f32_e32 v73, v97
	v_pk_mul_f32 v[60:61], v[194:195], v[52:53]
	v_pk_mul_f32 v[66:67], v[194:195], v[50:51]
	v_add_f32_e32 v50, v60, v61
	v_add_f32_e32 v51, v58, v59
	v_pk_mul_f32 v[68:69], v[194:195], v[54:55]
	v_pk_mul_f32 v[54:55], v[194:195], v[72:73]
	v_add_f32_e32 v51, v51, v50
	v_mov_b32_e32 v50, v61
	v_mov_b32_e32 v72, v61
	s_nop 1
	v_permlane32_swap_b32_e32 v50, v72
	v_exp_f32_e32 v53, v93
	v_cndmask_b32_e64 v93, v50, v72, s[38:39]
	v_cndmask_b32_e64 v80, v93, v217, s[38:39]
	v_add_f32_e32 v81, v51, v80
	s_nop 1
	v_mov_b32_dpp v84, v81 quad_perm:[1,0,3,2] row_mask:0xf bank_mask:0xf
	v_exp_f32_e32 v64, v88
	v_exp_f32_e32 v65, v89
	v_exp_f32_e32 v52, v92
	v_mov_b32_e32 v96, v63
	s_waitcnt lgkmcnt(0)
	v_add_f32_e32 v98, v81, v84
	s_nop 1
	v_mov_b32_dpp v99, v98 quad_perm:[2,3,0,1] row_mask:0xf bank_mask:0xf
	v_pk_mul_f32 v[64:65], v[194:195], v[64:65]
	v_pk_mul_f32 v[52:53], v[194:195], v[52:53]
	v_mov_b32_e32 v97, v63
	v_mov_b32_e32 v72, v67
	v_mov_b32_e32 v73, v67
	v_mov_b32_e32 v89, v69
	v_mov_b32_e32 v92, v69
	v_mov_b32_e32 v76, v57
	v_mov_b32_e32 v77, v57
	v_mov_b32_e32 v85, v65
	v_mov_b32_e32 v88, v65
	v_mov_b32_e32 v50, v53
	v_mov_b32_e32 v51, v53
	v_mov_b32_e32 v80, v55
	v_mov_b32_e32 v81, v55
	v_permlane32_swap_b32_e32 v96, v97
	v_permlane32_swap_b32_e32 v72, v73
	v_permlane32_swap_b32_e32 v89, v92
	v_permlane32_swap_b32_e32 v76, v77
	v_permlane32_swap_b32_e32 v85, v88
	v_permlane32_swap_b32_e32 v50, v51
	v_permlane32_swap_b32_e32 v80, v81
	v_lshl_add_u32 v84, s29, 6, v247
	s_and_saveexec_b64 s[0:1], s[40:41]
	s_cbranch_execz .LBB0_278
	s_waitcnt lgkmcnt(0)
	v_add_f32_e32 v98, v98, v99
	ds_write_b32 v84, v98 offset:43520
.LBB0_278:
	s_or_b64 exec, exec, s[0:1]
	v_exp_f32_e32 v70, v70
	v_exp_f32_e32 v71, v71
	v_add_f32_e32 v98, v62, v63
	v_cndmask_b32_e64 v96, v96, v97, s[38:39]
	v_cndmask_b32_e64 v93, v96, v93, s[38:39]
	v_pk_mul_f32 v[70:71], v[194:195], v[70:71]
	s_nop 0
	v_add_f32_e32 v97, v70, v71
	v_add_f32_e32 v97, v97, v98
	v_add_f32_e32 v93, v97, v93
	s_nop 1
	v_mov_b32_dpp v97, v93 quad_perm:[1,0,3,2] row_mask:0xf bank_mask:0xf
	s_waitcnt lgkmcnt(0)
	v_add_f32_e32 v93, v93, v97
	s_nop 1
	v_mov_b32_dpp v97, v93 quad_perm:[2,3,0,1] row_mask:0xf bank_mask:0xf
	s_and_saveexec_b64 s[0:1], s[40:41]
	s_cbranch_execz .LBB0_280
	s_waitcnt lgkmcnt(0)
	v_add_f32_e32 v93, v93, v97
	ds_write_b32 v84, v93 offset:43528
.LBB0_280:
	s_or_b64 exec, exec, s[0:1]
	v_exp_f32_e32 v74, v74
	v_exp_f32_e32 v75, v75
	v_cndmask_b32_e64 v93, v72, v73, s[38:39]
	s_waitcnt lgkmcnt(0)
	v_add_f32_e32 v97, v66, v67
	v_pk_mul_f32 v[72:73], v[194:195], v[74:75]
	s_nop 0
	v_add_f32_e32 v74, v72, v73
	v_add_f32_e32 v74, v74, v97
	v_cndmask_b32_e64 v75, v93, v96, s[38:39]
	v_add_f32_e32 v74, v74, v75
	s_nop 1
	v_mov_b32_dpp v75, v74 quad_perm:[1,0,3,2] row_mask:0xf bank_mask:0xf
	s_waitcnt lgkmcnt(0)
	v_add_f32_e32 v74, v74, v75
	s_nop 1
	v_mov_b32_dpp v75, v74 quad_perm:[2,3,0,1] row_mask:0xf bank_mask:0xf
	s_and_saveexec_b64 s[0:1], s[40:41]
	s_cbranch_execz .LBB0_282
	s_waitcnt lgkmcnt(0)
	v_add_f32_e32 v74, v74, v75
	ds_write_b32 v84, v74 offset:43536

; __device__ __forceinline__ float half_other(float x, int hl) { auto rr = __builtin_amdgcn_permlane32_swap(__float_as_uint(x), __float_as_uint(x), false, false); return hl ? __uint_as_float(rr[0]) : __uint_as_float(rr[1]); }
; template <int MODE> ...
;     ...
; #pragma unroll
;             for (int i = 0; i < 8; ++i) recv[i] = half_other(last[i], hl);
; #pragma unroll
;             for (int i = 0; i < 8; ++i) {
;                 const float prev = (i > 0) ? recv[i > 0 ? i - 1 : 0] : carry;
;                 float v = quad[i] + (hl ? recv[i] : prev);
;                 v += __shfl_xor(v, 1); v += __shfl_xor(v, 2);
;                 if ((n & 3) == 0) lds_st<float>(L + score_ofs + (16 * kt + 2 * i + hl) * 4, v);
;             }
;             carry = recv[7];
.LBB0_286:
	s_or_b64 exec, exec, s[0:1]
	v_exp_f32_e32 v78, v86
	s_waitcnt lgkmcnt(0)
	v_exp_f32_e32 v79, v87
	v_add_f32_e32 v86, v64, v65
	v_cndmask_b32_e64 v83, v85, v88, s[38:39]
	v_cndmask_b32_e64 v82, v83, v82, s[38:39]
	v_pk_mul_f32 v[78:79], v[194:195], v[78:79]
	s_nop 0
	v_add_f32_e32 v85, v78, v79
	v_add_f32_e32 v85, v85, v86
	v_add_f32_e32 v82, v85, v82
	s_nop 1
	v_mov_b32_dpp v85, v82 quad_perm:[1,0,3,2] row_mask:0xf bank_mask:0xf
	s_waitcnt lgkmcnt(0)
	v_add_f32_e32 v82, v82, v85
	s_nop 1
	v_mov_b32_dpp v85, v82 quad_perm:[2,3,0,1] row_mask:0xf bank_mask:0xf
	s_and_saveexec_b64 s[0:1], s[40:41]
	s_cbranch_execz .LBB0_288
	s_waitcnt lgkmcnt(0)
	v_add_f32_e32 v82, v82, v85
	ds_write_b32 v84, v82 offset:43560

; __device__ __forceinline__ float wave_sum(float v) {
; #pragma unroll
;     for (int o = 1; o < 64; o <<= 1) v += __shfl_xor(v, o);
;     return v;
; }
; __device__ __forceinline__ void ln_pass(const Params& P, const float* g, const float* b, const bool write_x) {
;     ...
;     for (int r0 = gw * 4; r0 < M; r0 += NGW * 4) {
;         f32x4 v[4][4];
; #pragma unroll
;         for (int q = 0; q < 4; ++q) {
;             const f32x4* xr = (const f32x4*)(P.out + (size_t)(r0 + q) * DM) + lane;
; #pragma unroll
;             for (int j = 0; j < 4; ++j) v[q][j] = xr[64 * j];
;         }
; #pragma unroll
;         for (int q = 0; q < 4; ++q) {
;             float s = 0.f;
; #pragma unroll
;             for (int j = 0; j < 4; ++j) s += (v[q][j][0] + v[q][j][1]) + (v[q][j][2] + v[q][j][3]);
;             const float mean = wave_sum(s) * (1.f / DM); float s2 = 0.f;
; #pragma unroll
;             for (int j = 0; j < 4; ++j) { v[q][j] = v[q][j] - mean; s2 += (v[q][j][0] * v[q][j][0] + v[q][j][1] * v[q][j][1]) + (v[q][j][2] * v[q][j][2] + v[q][j][3] * v[q][j][3]); }
;             const float rstd = 1.f / sqrtf(wave_sum(s2) * (1.f / DM) + LN_EPS);
;             if (lane == 0) { float2 st; st.x = mean; st.y = rstd; *(float2*)(stats + 2 * (size_t)(r0 + q)) = st; }
.LBB0_749:
	v_add_co_u32_e32 v34, vcc, 0xffffd000, v104
	s_mov_b32 s0, 0xf800000
	s_nop 0
	v_addc_co_u32_e32 v35, vcc, -1, v105, vcc
	global_load_dwordx4 v[94:97], v[34:35], off offset:-3072
	global_load_dwordx4 v[90:93], v[34:35], off offset:-2048
	global_load_dwordx4 v[86:89], v[34:35], off offset:-1024
	global_load_dwordx4 v[82:85], v[34:35], off
	v_add_co_u32_e32 v34, vcc, 0xffffe000, v104
	s_waitcnt vmcnt(0)
	v_mov_b32_e32 v106, v95
	v_mov_b32_e32 v107, v96
	v_mov_b32_e32 v108, v94
	v_mov_b32_e32 v109, v97
	v_pk_add_f32 v[106:107], v[106:107], v[108:109]
	v_mov_b32_e32 v108, v91
	v_mov_b32_e32 v109, v92
	v_mov_b32_e32 v110, v90
	v_mov_b32_e32 v111, v93
	v_pk_add_f32 v[108:109], v[108:109], v[110:111]
	v_add_f32_e32 v99, v106, v107
	v_pk_add_f32 v[108:109], v[108:109], v[108:109] op_sel:[0,1] op_sel_hi:[1,0]
	v_add_f32_e32 v106, 0, v99
	v_add_f32_e32 v110, v86, v87
	v_add_f32_e32 v112, v88, v89
	v_mov_b32_e32 v107, v82
	v_mov_b32_e32 v109, v83
	v_mov_b32_e32 v111, v84
	v_mov_b32_e32 v113, v85
	v_pk_add_f32 v[106:107], v[106:107], v[108:109]
	v_pk_add_f32 v[108:109], v[110:111], v[112:113]
	v_addc_co_u32_e32 v35, vcc, -1, v105, vcc
	v_pk_add_f32 v[106:107], v[106:107], v[108:109]
	global_load_dwordx4 v[78:81], v[34:35], off offset:-3072
	global_load_dwordx4 v[74:77], v[34:35], off offset:-2048
	global_load_dwordx4 v[70:73], v[34:35], off offset:-1024
	global_load_dwordx4 v[66:69], v[34:35], off
	v_add_f32_e32 v99, v106, v107
	v_add_co_u32_e32 v34, vcc, 0xfffff000, v104
	v_addc_co_u32_e32 v35, vcc, -1, v105, vcc
	global_load_dwordx4 v[62:65], v[34:35], off offset:-3072
	global_load_dwordx4 v[58:61], v[34:35], off offset:-2048
	global_load_dwordx4 v[54:57], v[34:35], off offset:-1024
	global_load_dwordx4 v[50:53], v[104:105], off offset:-4096
	global_load_dwordx4 v[46:49], v[104:105], off offset:-3072
	global_load_dwordx4 v[42:45], v[104:105], off offset:-2048
	global_load_dwordx4 v[38:41], v[104:105], off offset:-1024
	s_nop 0
	global_load_dwordx4 v[34:37], v[104:105], off
	s_nop 1
	v_add_f32_dpp v99, v99, v99 quad_perm:[1,0,3,2] row_mask:0xf bank_mask:0xf
	s_nop 1
	v_add_f32_dpp v99, v99, v99 quad_perm:[2,3,0,1] row_mask:0xf bank_mask:0xf
	s_nop 1
	v_add_f32_dpp v99, v99, v99 row_half_mirror row_mask:0xf bank_mask:0xf
	s_nop 1
	v_add_f32_dpp v99, v99, v99 row_mirror row_mask:0xf bank_mask:0xf
	s_nop 1
	v_add_f32_dpp v99, v99, v99 row_bcast:15 row_mask:0xa bank_mask:0xf
	s_nop 1
	v_add_f32_dpp v99, v99, v99 row_bcast:31 row_mask:0xc bank_mask:0xf
	s_nop 1
	v_readlane_b32 s98, v99, 63
	s_nop 2
	v_mov_b32_e32 v99, s98
	v_fmamk_f32 v97, v99, 0xba800000, v97
	v_fmamk_f32 v95, v99, 0xba800000, v95
	v_fmamk_f32 v113, v99, 0xba800000, v93
	v_fmamk_f32 v91, v99, 0xba800000, v91
	v_fmamk_f32 v96, v99, 0xba800000, v96
	v_fmac_f32_e32 v94, 0xba800000, v99
	v_mul_f32_e32 v106, v95, v95
	v_mul_f32_e32 v107, v97, v97
	v_fmamk_f32 v112, v99, 0xba800000, v92
	v_fmac_f32_e32 v90, 0xba800000, v99
	v_mul_f32_e32 v92, v91, v91
	v_mul_f32_e32 v93, v113, v113
	v_fmamk_f32 v111, v99, 0xba800000, v89
	v_fmamk_f32 v87, v99, 0xba800000, v87
	v_fmac_f32_e32 v106, v94, v94
	v_fmac_f32_e32 v107, v96, v96
	v_fmac_f32_e32 v92, v90, v90
	v_fmac_f32_e32 v93, v112, v112
	v_fmamk_f32 v110, v99, 0xba800000, v88
	v_fmac_f32_e32 v86, 0xba800000, v99
	v_mul_f32_e32 v88, v87, v87
	v_mul_f32_e32 v89, v111, v111
	v_fmamk_f32 v109, v99, 0xba800000, v85
	v_fmamk_f32 v83, v99, 0xba800000, v83
	v_add_f32_e32 v106, v106, v107
	v_add_f32_e32 v92, v92, v93
	v_fmac_f32_e32 v88, v86, v86
	v_fmac_f32_e32 v89, v110, v110
	v_fmamk_f32 v108, v99, 0xba800000, v84
	v_fmac_f32_e32 v82, 0xba800000, v99
	v_mul_f32_e32 v84, v83, v83
	v_mul_f32_e32 v85, v109, v109
	v_add_f32_e32 v92, v106, v92
	v_add_f32_e32 v88, v88, v89
	v_fmac_f32_e32 v84, v82, v82
	v_fmac_f32_e32 v85, v108, v108
	v_add_f32_e32 v88, v88, v92
	v_add_f32_e32 v84, v84, v85
	v_add_f32_e32 v84, v84, v88
	v_lshl_add_u64 v[106:107], s[20:21], 0, v[100:101]
	s_nop 1
	v_add_f32_dpp v84, v84, v84 quad_perm:[1,0,3,2] row_mask:0xf bank_mask:0xf
	s_nop 1
	v_add_f32_dpp v84, v84, v84 quad_perm:[2,3,0,1] row_mask:0xf bank_mask:0xf
	s_nop 1
	v_add_f32_dpp v84, v84, v84 row_half_mirror row_mask:0xf bank_mask:0xf
	s_nop 1
	v_add_f32_dpp v84, v84, v84 row_mirror row_mask:0xf bank_mask:0xf
	s_nop 1
	v_add_f32_dpp v84, v84, v84 row_bcast:15 row_mask:0xa bank_mask:0xf
	s_nop 1
	v_add_f32_dpp v84, v84, v84 row_bcast:31 row_mask:0xc bank_mask:0xf
	s_nop 1
	v_readlane_b32 s98, v84, 63
	s_nop 2
	v_mov_b32_e32 v84, s98
	v_fmamk_f32 v84, v84, 0x3a800000, v214
	v_cmp_gt_f32_e32 vcc, s0, v84
	v_mul_f32_e32 v85, 0x4f800000, v84
	s_nop 0
	v_cndmask_b32_e32 v84, v84, v85, vcc
	v_sqrt_f32_e32 v85, v84
	s_nop 0
	v_add_u32_e32 v88, -1, v85
	v_fma_f32 v89, -v88, v85, v84
	v_cmp_ge_f32_e64 s[0:1], 0, v89
	v_add_u32_e32 v89, 1, v85
	s_nop 0
	v_cndmask_b32_e64 v88, v85, v88, s[0:1]
	v_fma_f32 v85, -v89, v85, v84
	v_cmp_lt_f32_e64 s[0:1], 0, v85
	s_nop 1
	v_cndmask_b32_e64 v85, v88, v89, s[0:1]
	v_mul_f32_e32 v88, 0x37800000, v85
	v_cndmask_b32_e32 v85, v85, v88, vcc
	v_cmp_class_f32_e32 vcc, v84, v215
	s_nop 1
	v_cndmask_b32_e32 v84, v85, v84, vcc
	v_div_scale_f32 v85, s[0:1], v84, v84, 1.0
	v_rcp_f32_e32 v88, v85
	s_nop 0
	v_fma_f32 v89, -v85, v88, 1.0
	v_fmac_f32_e32 v88, v89, v88
	v_div_scale_f32 v89, vcc, 1.0, v84, 1.0
	v_mul_f32_e32 v92, v89, v88
	v_fma_f32 v93, -v85, v92, v89
	v_fmac_f32_e32 v92, v93, v88
	v_fma_f32 v85, -v85, v92, v89
	v_div_fmas_f32 v85, v85, v88, v92
	v_div_fixup_f32 v114, v85, v84, 1.0
	s_and_saveexec_b64 s[0:1], s[38:39]
	s_cbranch_execz .LBB0_751
	v_add_co_u32_e32 v88, vcc, 0x1bb00000, v106
	v_mul_f32_e32 v84, 0x3a800000, v99
	s_nop 0
	v_addc_co_u32_e32 v89, vcc, 0, v107, vcc
	v_mov_b32_e32 v85, v114
	global_store_dwordx2 v[88:89], v[84:85], off

; __device__ __forceinline__ unsigned cvt_pk(float lo, float hi) { f32x2_t v = {lo, hi}; bf16x2_t b = __builtin_convertvector(v, bf16x2_t); return __builtin_bit_cast(unsigned, b); }
; __device__ __forceinline__ float wave_sum(float v) {
; #pragma unroll
;     for (int o = 1; o < 64; o <<= 1) v += __shfl_xor(v, o);
;     return v;
; }
; __device__ __forceinline__ void ln_pass(const Params& P, const float* g, const float* b, const bool write_x) {
;     ...
;         for (int q = 0; q < 4; ++q) {
;             float s = 0.f;
; #pragma unroll
;             for (int j = 0; j < 4; ++j) s += (v[q][j][0] + v[q][j][1]) + (v[q][j][2] + v[q][j][3]);
;             const float mean = wave_sum(s) * (1.f / DM); float s2 = 0.f;
; #pragma unroll
;             for (int j = 0; j < 4; ++j) { v[q][j] = v[q][j] - mean; s2 += (v[q][j][0] * v[q][j][0] + v[q][j][1] * v[q][j][1]) + (v[q][j][2] * v[q][j][2] + v[q][j][3] * v[q][j][3]); }
;             const float rstd = 1.f / sqrtf(wave_sum(s2) * (1.f / DM) + LN_EPS);
;             if (lane == 0) { float2 st; st.x = mean; st.y = rstd; *(float2*)(stats + 2 * (size_t)(r0 + q)) = st; }
;             f32x4* xw = (f32x4*)(P.out + (size_t)(r0 + q) * DM) + lane;
;             u32x2* o8 = (u32x2*)((bf16_t*)(P.ws + WS_XN) + (size_t)(r0 + q) * DM) + lane;
; #pragma unroll
;             for (int j = 0; j < 4; ++j) {
;                 const f32x4 y = v[q][j] * rstd * gv[j] + bv[j];
;                 if (write_x) xw[64 * j] = y;
;                 u32x2 w; w.x = cvt_pk(y[0], y[1]); w.y = cvt_pk(y[2], y[3]); o8[64 * j] = w;
.LBB0_759:
	s_nop 1
	v_cvt_pk_bf16_f32 v82, v82, v83
	v_cvt_pk_bf16_f32 v83, v84, v85
	v_add_co_u32_e32 v84, vcc, 0x3600000, v96
	s_waitcnt vmcnt(13)
	v_mov_b32_e32 v86, v74
	v_addc_co_u32_e32 v85, vcc, 0, v97, vcc
	global_store_dwordx2 v[84:85], v[82:83], off offset:1536
	v_mov_b32_e32 v82, v79
	v_mov_b32_e32 v83, v80
	v_mov_b32_e32 v84, v78
	v_mov_b32_e32 v85, v81
	v_pk_add_f32 v[82:83], v[82:83], v[84:85]
	v_mov_b32_e32 v84, v75
	v_mov_b32_e32 v85, v76
	v_mov_b32_e32 v87, v77
	v_pk_add_f32 v[84:85], v[84:85], v[86:87]
	v_add_f32_e32 v82, v82, v83
	v_pk_add_f32 v[84:85], v[84:85], v[84:85] op_sel:[0,1] op_sel_hi:[1,0]
	v_add_f32_e32 v82, 0, v82
	s_waitcnt vmcnt(13)
	v_add_f32_e32 v86, v70, v71
	v_add_f32_e32 v88, v72, v73
	s_waitcnt vmcnt(12)
	v_mov_b32_e32 v83, v66
	v_mov_b32_e32 v85, v67
	v_mov_b32_e32 v87, v68
	v_mov_b32_e32 v89, v69
	v_pk_add_f32 v[82:83], v[82:83], v[84:85]
	v_pk_add_f32 v[84:85], v[86:87], v[88:89]
	s_mov_b32 s0, 0xf800000
	v_pk_add_f32 v[82:83], v[82:83], v[84:85]
	s_nop 0
	v_add_f32_e32 v82, v82, v83
	s_nop 1
	v_add_f32_dpp v82, v82, v82 quad_perm:[1,0,3,2] row_mask:0xf bank_mask:0xf
	s_nop 1
	v_add_f32_dpp v82, v82, v82 quad_perm:[2,3,0,1] row_mask:0xf bank_mask:0xf
	s_nop 1
	v_add_f32_dpp v82, v82, v82 row_half_mirror row_mask:0xf bank_mask:0xf
	s_nop 1
	v_add_f32_dpp v82, v82, v82 row_mirror row_mask:0xf bank_mask:0xf
	s_nop 1
	v_add_f32_dpp v82, v82, v82 row_bcast:15 row_mask:0xa bank_mask:0xf
	s_nop 1
	v_add_f32_dpp v82, v82, v82 row_bcast:31 row_mask:0xc bank_mask:0xf
	s_nop 1
	v_readlane_b32 s98, v82, 63
	s_nop 2
	v_mov_b32_e32 v89, s98
	v_fmamk_f32 v87, v89, 0xba800000, v81
	v_fmamk_f32 v79, v89, 0xba800000, v79
	v_fmamk_f32 v85, v89, 0xba800000, v77
	v_fmamk_f32 v75, v89, 0xba800000, v75
	v_fmamk_f32 v86, v89, 0xba800000, v80
	v_fmac_f32_e32 v78, 0xba800000, v89
	v_mul_f32_e32 v80, v79, v79
	v_mul_f32_e32 v81, v87, v87
	v_fmamk_f32 v84, v89, 0xba800000, v76
	v_fmac_f32_e32 v74, 0xba800000, v89
	v_mul_f32_e32 v76, v75, v75
	v_mul_f32_e32 v77, v85, v85
	v_fmac_f32_e32 v80, v78, v78
	v_fmac_f32_e32 v81, v86, v86
	v_fmac_f32_e32 v76, v74, v74
	v_fmac_f32_e32 v77, v84, v84
	v_fmamk_f32 v83, v89, 0xba800000, v73
	v_fmamk_f32 v71, v89, 0xba800000, v71
	v_add_f32_e32 v80, v80, v81
	v_add_f32_e32 v76, v76, v77
	v_fmamk_f32 v82, v89, 0xba800000, v72
	v_fmac_f32_e32 v70, 0xba800000, v89
	v_mul_f32_e32 v72, v71, v71
	v_mul_f32_e32 v73, v83, v83
	v_fmamk_f32 v81, v89, 0xba800000, v69
	v_fmamk_f32 v67, v89, 0xba800000, v67
	v_add_f32_e32 v76, v80, v76
	v_fmac_f32_e32 v72, v70, v70
	v_fmac_f32_e32 v73, v82, v82
	v_fmamk_f32 v80, v89, 0xba800000, v68
	v_fmac_f32_e32 v66, 0xba800000, v89
	v_mul_f32_e32 v68, v67, v67
	v_mul_f32_e32 v69, v81, v81
	v_add_f32_e32 v72, v72, v73
	v_fmac_f32_e32 v68, v66, v66
	v_fmac_f32_e32 v69, v80, v80
	v_add_f32_e32 v72, v72, v76
	v_add_f32_e32 v68, v68, v69
	v_add_f32_e32 v68, v68, v72
	s_nop 1
	v_add_f32_dpp v68, v68, v68 quad_perm:[1,0,3,2] row_mask:0xf bank_mask:0xf
	s_nop 1
	v_add_f32_dpp v68, v68, v68 quad_perm:[2,3,0,1] row_mask:0xf bank_mask:0xf
	s_nop 1
	v_add_f32_dpp v68, v68, v68 row_half_mirror row_mask:0xf bank_mask:0xf
	s_nop 1
	v_add_f32_dpp v68, v68, v68 row_mirror row_mask:0xf bank_mask:0xf
	s_nop 1
	v_add_f32_dpp v68, v68, v68 row_bcast:15 row_mask:0xa bank_mask:0xf
	s_nop 1
	v_add_f32_dpp v68, v68, v68 row_bcast:31 row_mask:0xc bank_mask:0xf
	s_nop 1
	v_readlane_b32 s98, v68, 63
	s_nop 2
	v_mov_b32_e32 v68, s98
	v_fmamk_f32 v68, v68, 0x3a800000, v214
	v_cmp_gt_f32_e32 vcc, s0, v68
	v_mul_f32_e32 v69, 0x4f800000, v68
	s_nop 0
	v_cndmask_b32_e32 v68, v68, v69, vcc
	v_sqrt_f32_e32 v69, v68
	s_nop 0
	v_add_u32_e32 v72, -1, v69
	v_fma_f32 v73, -v72, v69, v68
	v_cmp_ge_f32_e64 s[0:1], 0, v73
	v_add_u32_e32 v73, 1, v69
	s_nop 0
	v_cndmask_b32_e64 v72, v69, v72, s[0:1]
	v_fma_f32 v69, -v73, v69, v68
	v_cmp_lt_f32_e64 s[0:1], 0, v69
	s_nop 1
	v_cndmask_b32_e64 v69, v72, v73, s[0:1]
	v_mul_f32_e32 v72, 0x37800000, v69
	v_cndmask_b32_e32 v69, v69, v72, vcc
	v_cmp_class_f32_e32 vcc, v68, v215
	s_nop 1
	v_cndmask_b32_e32 v68, v69, v68, vcc
	v_div_scale_f32 v69, s[0:1], v68, v68, 1.0
	v_rcp_f32_e32 v72, v69
	s_nop 0
	v_fma_f32 v73, -v69, v72, 1.0
	v_fmac_f32_e32 v72, v73, v72
	v_div_scale_f32 v73, vcc, 1.0, v68, 1.0
	v_mul_f32_e32 v76, v73, v72
	v_fma_f32 v77, -v69, v76, v73
	v_fmac_f32_e32 v76, v77, v72
	v_fma_f32 v69, -v69, v76, v73
	v_div_fmas_f32 v69, v69, v72, v76
	v_div_fixup_f32 v88, v69, v68, 1.0
	s_and_saveexec_b64 s[0:1], s[38:39]
	s_cbranch_execz .LBB0_761
	v_add_co_u32_e32 v72, vcc, 0x1bb00000, v106
	v_mul_f32_e32 v68, 0x3a800000, v89
	s_nop 0
	v_addc_co_u32_e32 v73, vcc, 0, v107, vcc
	v_mov_b32_e32 v69, v88
	global_store_dwordx2 v[72:73], v[68:69], off offset:8

; __device__ __forceinline__ unsigned cvt_pk(float lo, float hi) { f32x2_t v = {lo, hi}; bf16x2_t b = __builtin_convertvector(v, bf16x2_t); return __builtin_bit_cast(unsigned, b); }
; __device__ __forceinline__ float wave_sum(float v) {
; #pragma unroll
;     for (int o = 1; o < 64; o <<= 1) v += __shfl_xor(v, o);
;     return v;
; }
; __device__ __forceinline__ void ln_pass(const Params& P, const float* g, const float* b, const bool write_x) {
;     ...
;         for (int q = 0; q < 4; ++q) {
;             float s = 0.f;
; #pragma unroll
;             for (int j = 0; j < 4; ++j) s += (v[q][j][0] + v[q][j][1]) + (v[q][j][2] + v[q][j][3]);
;             const float mean = wave_sum(s) * (1.f / DM); float s2 = 0.f;
; #pragma unroll
;             for (int j = 0; j < 4; ++j) { v[q][j] = v[q][j] - mean; s2 += (v[q][j][0] * v[q][j][0] + v[q][j][1] * v[q][j][1]) + (v[q][j][2] * v[q][j][2] + v[q][j][3] * v[q][j][3]); }
;             const float rstd = 1.f / sqrtf(wave_sum(s2) * (1.f / DM) + LN_EPS);
;             if (lane == 0) { float2 st; st.x = mean; st.y = rstd; *(float2*)(stats + 2 * (size_t)(r0 + q)) = st; }
;             f32x4* xw = (f32x4*)(P.out + (size_t)(r0 + q) * DM) + lane;
;             u32x2* o8 = (u32x2*)((bf16_t*)(P.ws + WS_XN) + (size_t)(r0 + q) * DM) + lane;
; #pragma unroll
;             for (int j = 0; j < 4; ++j) {
;                 const f32x4 y = v[q][j] * rstd * gv[j] + bv[j];
;                 if (write_x) xw[64 * j] = y;
;                 u32x2 w; w.x = cvt_pk(y[0], y[1]); w.y = cvt_pk(y[2], y[3]); o8[64 * j] = w;
.LBB0_769:
	s_nop 1
	v_cvt_pk_bf16_f32 v66, v66, v67
	v_cvt_pk_bf16_f32 v67, v68, v69
	v_add_co_u32_e32 v68, vcc, 0x3600000, v96
	s_waitcnt vmcnt(13)
	v_mov_b32_e32 v70, v58
	v_addc_co_u32_e32 v69, vcc, 0, v97, vcc
	global_store_dwordx2 v[68:69], v[66:67], off offset:3584
	v_mov_b32_e32 v66, v63
	v_mov_b32_e32 v67, v64
	v_mov_b32_e32 v68, v62
	v_mov_b32_e32 v69, v65
	v_pk_add_f32 v[66:67], v[66:67], v[68:69]
	v_mov_b32_e32 v68, v59
	v_mov_b32_e32 v69, v60
	v_mov_b32_e32 v71, v61
	v_pk_add_f32 v[68:69], v[68:69], v[70:71]
	v_add_f32_e32 v66, v66, v67
	v_pk_add_f32 v[68:69], v[68:69], v[68:69] op_sel:[0,1] op_sel_hi:[1,0]
	v_add_f32_e32 v66, 0, v66
	s_waitcnt vmcnt(13)
	v_add_f32_e32 v70, v54, v55
	v_add_f32_e32 v72, v56, v57
	s_waitcnt vmcnt(12)
	v_mov_b32_e32 v67, v50
	v_mov_b32_e32 v69, v51
	v_mov_b32_e32 v71, v52
	v_mov_b32_e32 v73, v53
	v_pk_add_f32 v[66:67], v[66:67], v[68:69]
	v_pk_add_f32 v[68:69], v[70:71], v[72:73]
	s_mov_b32 s0, 0xf800000
	v_pk_add_f32 v[66:67], v[66:67], v[68:69]
	s_nop 0
	v_add_f32_e32 v66, v66, v67
	s_nop 1
	v_add_f32_dpp v66, v66, v66 quad_perm:[1,0,3,2] row_mask:0xf bank_mask:0xf
	s_nop 1
	v_add_f32_dpp v66, v66, v66 quad_perm:[2,3,0,1] row_mask:0xf bank_mask:0xf
	s_nop 1
	v_add_f32_dpp v66, v66, v66 row_half_mirror row_mask:0xf bank_mask:0xf
	s_nop 1
	v_add_f32_dpp v66, v66, v66 row_mirror row_mask:0xf bank_mask:0xf
	s_nop 1
	v_add_f32_dpp v66, v66, v66 row_bcast:15 row_mask:0xa bank_mask:0xf
	s_nop 1
	v_add_f32_dpp v66, v66, v66 row_bcast:31 row_mask:0xc bank_mask:0xf
	s_nop 1
	v_readlane_b32 s98, v66, 63
	s_nop 2
	v_mov_b32_e32 v73, s98
	v_fmamk_f32 v71, v73, 0xba800000, v65
	v_fmamk_f32 v63, v73, 0xba800000, v63
	v_fmamk_f32 v69, v73, 0xba800000, v61
	v_fmamk_f32 v59, v73, 0xba800000, v59
	v_fmamk_f32 v70, v73, 0xba800000, v64
	v_fmac_f32_e32 v62, 0xba800000, v73
	v_mul_f32_e32 v64, v63, v63
	v_mul_f32_e32 v65, v71, v71
	v_fmamk_f32 v68, v73, 0xba800000, v60
	v_fmac_f32_e32 v58, 0xba800000, v73
	v_mul_f32_e32 v60, v59, v59
	v_mul_f32_e32 v61, v69, v69
	v_fmac_f32_e32 v64, v62, v62
	v_fmac_f32_e32 v65, v70, v70
	v_fmac_f32_e32 v60, v58, v58
	v_fmac_f32_e32 v61, v68, v68
	v_fmamk_f32 v67, v73, 0xba800000, v57
	v_fmamk_f32 v55, v73, 0xba800000, v55
	v_add_f32_e32 v64, v64, v65
	v_add_f32_e32 v60, v60, v61
	v_fmamk_f32 v66, v73, 0xba800000, v56
	v_fmac_f32_e32 v54, 0xba800000, v73
	v_mul_f32_e32 v56, v55, v55
	v_mul_f32_e32 v57, v67, v67
	v_fmamk_f32 v65, v73, 0xba800000, v53
	v_fmamk_f32 v51, v73, 0xba800000, v51
	v_add_f32_e32 v60, v64, v60
	v_fmac_f32_e32 v56, v54, v54
	v_fmac_f32_e32 v57, v66, v66
	v_fmamk_f32 v64, v73, 0xba800000, v52
	v_fmac_f32_e32 v50, 0xba800000, v73
	v_mul_f32_e32 v52, v51, v51
	v_mul_f32_e32 v53, v65, v65
	v_add_f32_e32 v56, v56, v57
	v_fmac_f32_e32 v52, v50, v50
	v_fmac_f32_e32 v53, v64, v64
	v_add_f32_e32 v56, v56, v60
	v_add_f32_e32 v52, v52, v53
	v_add_f32_e32 v52, v52, v56
	s_nop 1
	v_add_f32_dpp v52, v52, v52 quad_perm:[1,0,3,2] row_mask:0xf bank_mask:0xf
	s_nop 1
	v_add_f32_dpp v52, v52, v52 quad_perm:[2,3,0,1] row_mask:0xf bank_mask:0xf
	s_nop 1
	v_add_f32_dpp v52, v52, v52 row_half_mirror row_mask:0xf bank_mask:0xf
	s_nop 1
	v_add_f32_dpp v52, v52, v52 row_mirror row_mask:0xf bank_mask:0xf
	s_nop 1
	v_add_f32_dpp v52, v52, v52 row_bcast:15 row_mask:0xa bank_mask:0xf
	s_nop 1
	v_add_f32_dpp v52, v52, v52 row_bcast:31 row_mask:0xc bank_mask:0xf
	s_nop 1
	v_readlane_b32 s98, v52, 63
	s_nop 2
	v_mov_b32_e32 v52, s98
	v_fmamk_f32 v52, v52, 0x3a800000, v214
	v_cmp_gt_f32_e32 vcc, s0, v52
	v_mul_f32_e32 v53, 0x4f800000, v52
	s_nop 0
	v_cndmask_b32_e32 v52, v52, v53, vcc
	v_sqrt_f32_e32 v53, v52
	s_nop 0
	v_add_u32_e32 v56, -1, v53
	v_fma_f32 v57, -v56, v53, v52
	v_cmp_ge_f32_e64 s[0:1], 0, v57
	v_add_u32_e32 v57, 1, v53
	s_nop 0
	v_cndmask_b32_e64 v56, v53, v56, s[0:1]
	v_fma_f32 v53, -v57, v53, v52
	v_cmp_lt_f32_e64 s[0:1], 0, v53
	s_nop 1
	v_cndmask_b32_e64 v53, v56, v57, s[0:1]
	v_mul_f32_e32 v56, 0x37800000, v53
	v_cndmask_b32_e32 v53, v53, v56, vcc
	v_cmp_class_f32_e32 vcc, v52, v215
	s_nop 1
	v_cndmask_b32_e32 v52, v53, v52, vcc
	v_div_scale_f32 v53, s[0:1], v52, v52, 1.0
	v_rcp_f32_e32 v56, v53
	s_nop 0
	v_fma_f32 v57, -v53, v56, 1.0
	v_fmac_f32_e32 v56, v57, v56
	v_div_scale_f32 v57, vcc, 1.0, v52, 1.0
	v_mul_f32_e32 v60, v57, v56
	v_fma_f32 v61, -v53, v60, v57
	v_fmac_f32_e32 v60, v61, v56
	v_fma_f32 v53, -v53, v60, v57
	v_div_fmas_f32 v53, v53, v56, v60
	v_div_fixup_f32 v72, v53, v52, 1.0
	s_and_saveexec_b64 s[0:1], s[38:39]
	s_cbranch_execz .LBB0_771
	v_add_co_u32_e32 v56, vcc, 0x1bb00000, v106
	v_mul_f32_e32 v52, 0x3a800000, v73
	s_nop 0
	v_addc_co_u32_e32 v57, vcc, 0, v107, vcc
	v_mov_b32_e32 v53, v72
	global_store_dwordx2 v[56:57], v[52:53], off offset:16

; __device__ __forceinline__ unsigned cvt_pk(float lo, float hi) { f32x2_t v = {lo, hi}; bf16x2_t b = __builtin_convertvector(v, bf16x2_t); return __builtin_bit_cast(unsigned, b); }
; __device__ __forceinline__ float wave_sum(float v) {
; #pragma unroll
;     for (int o = 1; o < 64; o <<= 1) v += __shfl_xor(v, o);
;     return v;
; }
; __device__ __forceinline__ void ln_pass(const Params& P, const float* g, const float* b, const bool write_x) {
;     ...
;         for (int q = 0; q < 4; ++q) {
;             float s = 0.f;
; #pragma unroll
;             for (int j = 0; j < 4; ++j) s += (v[q][j][0] + v[q][j][1]) + (v[q][j][2] + v[q][j][3]);
;             const float mean = wave_sum(s) * (1.f / DM); float s2 = 0.f;
; #pragma unroll
;             for (int j = 0; j < 4; ++j) { v[q][j] = v[q][j] - mean; s2 += (v[q][j][0] * v[q][j][0] + v[q][j][1] * v[q][j][1]) + (v[q][j][2] * v[q][j][2] + v[q][j][3] * v[q][j][3]); }
;             const float rstd = 1.f / sqrtf(wave_sum(s2) * (1.f / DM) + LN_EPS);
;             if (lane == 0) { float2 st; st.x = mean; st.y = rstd; *(float2*)(stats + 2 * (size_t)(r0 + q)) = st; }
;             f32x4* xw = (f32x4*)(P.out + (size_t)(r0 + q) * DM) + lane;
;             u32x2* o8 = (u32x2*)((bf16_t*)(P.ws + WS_XN) + (size_t)(r0 + q) * DM) + lane;
; #pragma unroll
;             for (int j = 0; j < 4; ++j) {
;                 const f32x4 y = v[q][j] * rstd * gv[j] + bv[j];
;                 if (write_x) xw[64 * j] = y;
;                 u32x2 w; w.x = cvt_pk(y[0], y[1]); w.y = cvt_pk(y[2], y[3]); o8[64 * j] = w;
.LBB0_779:
	s_nop 1
	v_cvt_pk_bf16_f32 v50, v50, v51
	v_cvt_pk_bf16_f32 v51, v52, v53
	v_add_co_u32_e32 v52, vcc, 0x3601000, v96
	s_waitcnt vmcnt(13)
	v_mov_b32_e32 v54, v42
	v_addc_co_u32_e32 v53, vcc, 0, v97, vcc
	global_store_dwordx2 v[52:53], v[50:51], off offset:1536
	v_mov_b32_e32 v50, v47
	v_mov_b32_e32 v51, v48
	v_mov_b32_e32 v52, v46
	v_mov_b32_e32 v53, v49
	v_pk_add_f32 v[50:51], v[50:51], v[52:53]
	v_mov_b32_e32 v52, v43
	v_mov_b32_e32 v53, v44
	v_mov_b32_e32 v55, v45
	v_pk_add_f32 v[52:53], v[52:53], v[54:55]
	v_add_f32_e32 v50, v50, v51
	v_pk_add_f32 v[52:53], v[52:53], v[52:53] op_sel:[0,1] op_sel_hi:[1,0]
	v_add_f32_e32 v50, 0, v50
	s_waitcnt vmcnt(13)
	v_add_f32_e32 v54, v38, v39
	v_add_f32_e32 v56, v40, v41
	s_waitcnt vmcnt(12)
	v_mov_b32_e32 v51, v34
	v_mov_b32_e32 v53, v35
	v_mov_b32_e32 v55, v36
	v_mov_b32_e32 v57, v37
	v_pk_add_f32 v[50:51], v[50:51], v[52:53]
	v_pk_add_f32 v[52:53], v[54:55], v[56:57]
	s_mov_b32 s0, 0xf800000
	v_pk_add_f32 v[50:51], v[50:51], v[52:53]
	s_nop 0
	v_add_f32_e32 v50, v50, v51
	s_nop 1
	v_add_f32_dpp v50, v50, v50 quad_perm:[1,0,3,2] row_mask:0xf bank_mask:0xf
	s_nop 1
	v_add_f32_dpp v50, v50, v50 quad_perm:[2,3,0,1] row_mask:0xf bank_mask:0xf
	s_nop 1
	v_add_f32_dpp v50, v50, v50 row_half_mirror row_mask:0xf bank_mask:0xf
	s_nop 1
	v_add_f32_dpp v50, v50, v50 row_mirror row_mask:0xf bank_mask:0xf
	s_nop 1
	v_add_f32_dpp v50, v50, v50 row_bcast:15 row_mask:0xa bank_mask:0xf
	s_nop 1
	v_add_f32_dpp v50, v50, v50 row_bcast:31 row_mask:0xc bank_mask:0xf
	s_nop 1
	v_readlane_b32 s98, v50, 63
	s_nop 2
	v_mov_b32_e32 v57, s98
	v_fmamk_f32 v55, v57, 0xba800000, v49
	v_fmamk_f32 v47, v57, 0xba800000, v47
	v_fmamk_f32 v53, v57, 0xba800000, v45
	v_fmamk_f32 v43, v57, 0xba800000, v43
	v_fmamk_f32 v54, v57, 0xba800000, v48
	v_fmac_f32_e32 v46, 0xba800000, v57
	v_mul_f32_e32 v48, v47, v47
	v_mul_f32_e32 v49, v55, v55
	v_fmamk_f32 v52, v57, 0xba800000, v44
	v_fmac_f32_e32 v42, 0xba800000, v57
	v_mul_f32_e32 v44, v43, v43
	v_mul_f32_e32 v45, v53, v53
	v_fmac_f32_e32 v48, v46, v46
	v_fmac_f32_e32 v49, v54, v54
	v_fmac_f32_e32 v44, v42, v42
	v_fmac_f32_e32 v45, v52, v52
	v_fmamk_f32 v51, v57, 0xba800000, v41
	v_fmamk_f32 v39, v57, 0xba800000, v39
	v_add_f32_e32 v48, v48, v49
	v_add_f32_e32 v44, v44, v45
	v_fmamk_f32 v50, v57, 0xba800000, v40
	v_fmac_f32_e32 v38, 0xba800000, v57
	v_mul_f32_e32 v40, v39, v39
	v_mul_f32_e32 v41, v51, v51
	v_fmamk_f32 v49, v57, 0xba800000, v37
	v_fmamk_f32 v35, v57, 0xba800000, v35
	v_add_f32_e32 v44, v48, v44
	v_fmac_f32_e32 v40, v38, v38
	v_fmac_f32_e32 v41, v50, v50
	v_fmamk_f32 v48, v57, 0xba800000, v36
	v_fmac_f32_e32 v34, 0xba800000, v57
	v_mul_f32_e32 v36, v35, v35
	v_mul_f32_e32 v37, v49, v49
	v_add_f32_e32 v40, v40, v41
	v_fmac_f32_e32 v36, v34, v34
	v_fmac_f32_e32 v37, v48, v48
	v_add_f32_e32 v40, v40, v44
	v_add_f32_e32 v36, v36, v37
	v_add_f32_e32 v36, v36, v40
	s_nop 1
	v_add_f32_dpp v36, v36, v36 quad_perm:[1,0,3,2] row_mask:0xf bank_mask:0xf
	s_nop 1
	v_add_f32_dpp v36, v36, v36 quad_perm:[2,3,0,1] row_mask:0xf bank_mask:0xf
	s_nop 1
	v_add_f32_dpp v36, v36, v36 row_half_mirror row_mask:0xf bank_mask:0xf
	s_nop 1
	v_add_f32_dpp v36, v36, v36 row_mirror row_mask:0xf bank_mask:0xf
	s_nop 1
	v_add_f32_dpp v36, v36, v36 row_bcast:15 row_mask:0xa bank_mask:0xf
	s_nop 1
	v_add_f32_dpp v36, v36, v36 row_bcast:31 row_mask:0xc bank_mask:0xf
	s_nop 1
	v_readlane_b32 s98, v36, 63
	s_nop 2
	v_mov_b32_e32 v36, s98
	v_fmamk_f32 v36, v36, 0x3a800000, v214
	v_cmp_gt_f32_e32 vcc, s0, v36
	v_mul_f32_e32 v37, 0x4f800000, v36
	s_nop 0
	v_cndmask_b32_e32 v36, v36, v37, vcc
	v_sqrt_f32_e32 v37, v36
	s_nop 0
	v_add_u32_e32 v40, -1, v37
	v_fma_f32 v41, -v40, v37, v36
	v_cmp_ge_f32_e64 s[0:1], 0, v41
	v_add_u32_e32 v41, 1, v37
	s_nop 0
	v_cndmask_b32_e64 v40, v37, v40, s[0:1]
	v_fma_f32 v37, -v41, v37, v36
	v_cmp_lt_f32_e64 s[0:1], 0, v37
	s_nop 1
	v_cndmask_b32_e64 v37, v40, v41, s[0:1]
	v_mul_f32_e32 v40, 0x37800000, v37
	v_cndmask_b32_e32 v37, v37, v40, vcc
	v_cmp_class_f32_e32 vcc, v36, v215
	s_nop 1
	v_cndmask_b32_e32 v36, v37, v36, vcc
	v_div_scale_f32 v37, s[0:1], v36, v36, 1.0
	v_rcp_f32_e32 v40, v37
	s_nop 0
	v_fma_f32 v41, -v37, v40, 1.0
	v_fmac_f32_e32 v40, v41, v40
	v_div_scale_f32 v41, vcc, 1.0, v36, 1.0
	v_mul_f32_e32 v44, v41, v40
	v_fma_f32 v45, -v37, v44, v41
	v_fmac_f32_e32 v44, v45, v40
	v_fma_f32 v37, -v37, v44, v41
	v_div_fmas_f32 v37, v37, v40, v44
	v_div_fixup_f32 v56, v37, v36, 1.0
	s_and_saveexec_b64 s[0:1], s[38:39]
	s_cbranch_execz .LBB0_781
	v_add_co_u32_e32 v40, vcc, 0x1bb00000, v106
	v_mul_f32_e32 v36, 0x3a800000, v57
	s_nop 0
	v_addc_co_u32_e32 v41, vcc, 0, v107, vcc
	v_mov_b32_e32 v37, v56
	global_store_dwordx2 v[40:41], v[36:37], off offset:24
